# rstd/bias table staging of input-projection and ffn-up: all units' loads issued before one wait (was one round trip per unit)
# baseline (speedup 1.0000x reference)
; __device__ __forceinline__ float rsq(float x) { return __builtin_amdgcn_rsqf(x); }
;     __device__ bool next(int i, Unit& u) const {
;         const long L = (long)i * G + c; if (L >= nwg) return false;
;         int wgid = (int)L; { const int q = nwg / NXCD, r = nwg % NXCD, xcd = wgid % NXCD, off = wgid / NXCD; wgid = (xcd < r ? xcd * (q + 1) : r * (q + 1) + (xcd - r) * q) + off; }
;         const int nig = WGM * nN, gid = wgid / nig, fm = gid * WGM, gsz = (nM - fm) < WGM ? (nM - fm) : WGM;
;         u.pm = fm + ((wgid % nig) % gsz); u.pn = (wgid % nig) / gsz; return true;
;     }
; template <class EpiT, class Sched>
; __device__ __forceinline__ void gemm_phase(LAS unsigned char* lds, const Gemm g, const Sched& S, const EpiT& E, int wv) {
;     ...
;     if constexpr (EpiT::TAB) {
;         Unit tu;
;         for (int i = 0; S.next(i, tu); ++i) {
;             if (tid < 256) { const f32x4* pp = (const f32x4*)(E.partr + (size_t)(tu.pm * BM + tid) * 16); const f32x4 p0 = pp[0], p1 = pp[1], p2 = pp[2], p3 = pp[3];
;                 const f32x4 ps = (p0 + p1) + (p2 + p3); tab[i * 512 + tid] = rsq(((ps[0] + ps[1]) + (ps[2] + ps[3])) * (1.f / DM) + EPS); }
;             else { const int mr = (tu.pm * BM < MX) ? ((tu.pm * BM) >> 11) : 8; tab[i * 512 + tid] = E.bias[(size_t)mr * E.bias_ld + tu.pn * BM + (tid - 256)]; }
;         }
.LBB0_229:
	s_andn2_b64 vcc, exec, s[2:3]
	s_cbranch_vccnz .LBB0_317
	s_waitcnt lgkmcnt(0)
	s_add_u32 s8, s0, 0x1fa00000
	s_movk_i32 s2, 0xff
	v_readlane_b32 s5, v255, 22
	s_addc_u32 s9, s1, 0
	v_cmp_lt_i32_e64 s[2:3], s2, v192
	v_lshl_add_u32 v0, v192, 2, s5
	s_mov_b64 s[10:11], s[6:7]
	s_mov_b32 s22, 0
	v_cmp_gt_i64_e32 vcc, s[10:11], v[194:195]
	s_nop 1
	s_cbranch_vccnz .Ltab1_wait
	s_ashr_i32 s5, s10, 31
	s_lshr_b32 s5, s5, 29
	s_add_i32 s5, s10, s5
	s_ashr_i32 s12, s5, 3
	s_and_b32 s5, s5, -8
	s_sub_i32 s5, s10, s5
	s_cmp_lt_i32 s5, 0
	s_movk_i32 s13, 0x12a
	s_cselect_b32 s13, s13, 0x129
	s_mul_i32 s5, s5, s13
	s_add_i32 s5, s5, s12
	s_mul_hi_i32 s12, s5, 0x3e0f83e1
	s_lshr_b32 s13, s12, 31
	s_ashr_i32 s12, s12, 6
	s_add_i32 s12, s12, s13
	s_lshl_b32 s13, s12, 3
	s_sub_i32 s15, 0x48, s13
	s_min_i32 s16, s15, 8
	s_abs_i32 s15, s16
	v_cvt_f32_u32_e32 v1, s15
	s_sub_i32 s18, 0, s15
	s_mulk_i32 s12, 0x108
	s_sub_i32 s5, s5, s12
	v_rcp_iflag_f32_e32 v1, v1
	s_abs_i32 s12, s5
	s_xor_b32 s17, s5, s16
	s_ashr_i32 s17, s17, 31
	v_mul_f32_e32 v1, 0x4f7ffffe, v1
	v_cvt_u32_f32_e32 v1, v1
	s_nop 0
	v_readfirstlane_b32 s19, v1
	s_mul_i32 s18, s18, s19
	s_mul_hi_u32 s18, s19, s18
	s_add_i32 s19, s19, s18
	s_mul_hi_u32 s18, s12, s19
	s_mul_i32 s19, s18, s15
	s_sub_i32 s12, s12, s19
	s_add_i32 s20, s18, 1
	s_sub_i32 s19, s12, s15
	s_cmp_ge_u32 s12, s15
	s_cselect_b32 s18, s20, s18
	s_cselect_b32 s12, s19, s12
	s_add_i32 s19, s18, 1
	s_cmp_ge_u32 s12, s15
	s_cselect_b32 s12, s19, s18
	s_xor_b32 s12, s12, s17
	s_sub_i32 s15, s12, s17
	s_mul_i32 s12, s15, s16
	s_sub_i32 s5, s5, s12
	s_add_i32 s5, s13, s5
	s_and_b64 vcc, exec, s[2:3]
	s_cbranch_vccz .Ltab1_r0
	s_min_i32 s16, s5, 64
	s_ashr_i32 s18, s16, 3
	s_lshl_b32 s16, s15, 8
	s_ashr_i32 s17, s16, 31
	s_mul_hi_i32 s15, s18, 0x8400
	s_mul_i32 s18, s18, 0x8400
	s_add_u32 s18, s0, s18
	s_addc_u32 s15, s1, s15
	s_lshl_b64 s[16:17], s[16:17], 2
	s_add_u32 s16, s18, s16
	s_addc_u32 s17, s15, s17
	v_lshl_add_u64 v[2:3], v[192:193], 2, s[16:17]
	v_add_co_u32_e32 v2, vcc, 0x317f000, v2
	s_nop 1
	v_addc_co_u32_e32 v3, vcc, 0, v3, vcc
	global_load_dword v16, v[2:3], off offset:3072
	s_branch .Ltab1_n0
.Ltab1_r0:
	v_lshl_add_u32 v2, s5, 8, v192
	v_ashrrev_i32_e32 v3, 31, v2
	v_lshlrev_b64 v[2:3], 6, v[2:3]
	v_lshl_add_u64 v[6:7], s[8:9], 0, v[2:3]
	global_load_dwordx4 v[16:19], v[6:7], off
	global_load_dwordx4 v[20:23], v[6:7], off offset:16
	global_load_dwordx4 v[24:27], v[6:7], off offset:32
	global_load_dwordx4 v[28:31], v[6:7], off offset:48
.Ltab1_n0:
	s_add_u32 s10, s10, s60
	s_addc_u32 s11, s11, s78
	s_add_i32 s22, s22, 1
	v_cmp_gt_i64_e32 vcc, s[10:11], v[194:195]
	s_nop 1
	s_cbranch_vccnz .Ltab1_wait
	s_ashr_i32 s5, s10, 31
	s_lshr_b32 s5, s5, 29
	s_add_i32 s5, s10, s5
	s_ashr_i32 s12, s5, 3
	s_and_b32 s5, s5, -8
	s_sub_i32 s5, s10, s5
	s_cmp_lt_i32 s5, 0
	s_movk_i32 s13, 0x12a
	s_cselect_b32 s13, s13, 0x129
	s_mul_i32 s5, s5, s13
	s_add_i32 s5, s5, s12
	s_mul_hi_i32 s12, s5, 0x3e0f83e1
	s_lshr_b32 s13, s12, 31
	s_ashr_i32 s12, s12, 6
	s_add_i32 s12, s12, s13
	s_lshl_b32 s13, s12, 3
	s_sub_i32 s15, 0x48, s13
	s_min_i32 s16, s15, 8
	s_abs_i32 s15, s16
	v_cvt_f32_u32_e32 v1, s15
	s_sub_i32 s18, 0, s15
	s_mulk_i32 s12, 0x108
	s_sub_i32 s5, s5, s12
	v_rcp_iflag_f32_e32 v1, v1
	s_abs_i32 s12, s5
	s_xor_b32 s17, s5, s16
	s_ashr_i32 s17, s17, 31
	v_mul_f32_e32 v1, 0x4f7ffffe, v1
	v_cvt_u32_f32_e32 v1, v1
	s_nop 0
	v_readfirstlane_b32 s19, v1
	s_mul_i32 s18, s18, s19
	s_mul_hi_u32 s18, s19, s18
	s_add_i32 s19, s19, s18
	s_mul_hi_u32 s18, s12, s19
	s_mul_i32 s19, s18, s15
	s_sub_i32 s12, s12, s19
	s_add_i32 s20, s18, 1
	s_sub_i32 s19, s12, s15
	s_cmp_ge_u32 s12, s15
	s_cselect_b32 s18, s20, s18
	s_cselect_b32 s12, s19, s12
	s_add_i32 s19, s18, 1
	s_cmp_ge_u32 s12, s15
	s_cselect_b32 s12, s19, s18
	s_xor_b32 s12, s12, s17
	s_sub_i32 s15, s12, s17
	s_mul_i32 s12, s15, s16
	s_sub_i32 s5, s5, s12
	s_add_i32 s5, s13, s5
	s_and_b64 vcc, exec, s[2:3]
	s_cbranch_vccz .Ltab1_r1
	s_min_i32 s16, s5, 64
	s_ashr_i32 s18, s16, 3
	s_lshl_b32 s16, s15, 8
	s_ashr_i32 s17, s16, 31
	s_mul_hi_i32 s15, s18, 0x8400
	s_mul_i32 s18, s18, 0x8400
	s_add_u32 s18, s0, s18
	s_addc_u32 s15, s1, s15
	s_lshl_b64 s[16:17], s[16:17], 2
	s_add_u32 s16, s18, s16
	s_addc_u32 s17, s15, s17
	v_lshl_add_u64 v[2:3], v[192:193], 2, s[16:17]
	v_add_co_u32_e32 v2, vcc, 0x317f000, v2
	s_nop 1
	v_addc_co_u32_e32 v3, vcc, 0, v3, vcc
	global_load_dword v32, v[2:3], off offset:3072
	s_branch .Ltab1_n1
.Ltab1_r1:
	v_lshl_add_u32 v2, s5, 8, v192
	v_ashrrev_i32_e32 v3, 31, v2
	v_lshlrev_b64 v[2:3], 6, v[2:3]
	v_lshl_add_u64 v[6:7], s[8:9], 0, v[2:3]
	global_load_dwordx4 v[32:35], v[6:7], off
	global_load_dwordx4 v[36:39], v[6:7], off offset:16
	global_load_dwordx4 v[40:43], v[6:7], off offset:32
	global_load_dwordx4 v[44:47], v[6:7], off offset:48
; __device__ __forceinline__ float rsq(float x) { return __builtin_amdgcn_rsqf(x); }
;     __device__ bool next(int i, Unit& u) const {
;         const long L = (long)i * G + c; if (L >= nwg) return false;
;         int wgid = (int)L; { const int q = nwg / NXCD, r = nwg % NXCD, xcd = wgid % NXCD, off = wgid / NXCD; wgid = (xcd < r ? xcd * (q + 1) : r * (q + 1) + (xcd - r) * q) + off; }
;         const int nig = WGM * nN, gid = wgid / nig, fm = gid * WGM, gsz = (nM - fm) < WGM ? (nM - fm) : WGM;
;         u.pm = fm + ((wgid % nig) % gsz); u.pn = (wgid % nig) / gsz; return true;
;     }
; template <class EpiT, class Sched>
; __device__ __forceinline__ void gemm_phase(LAS unsigned char* lds, const Gemm g, const Sched& S, const EpiT& E, int wv) {
;     ...
;     if constexpr (EpiT::TAB) {
;         Unit tu;
;         for (int i = 0; S.next(i, tu); ++i) {
;             if (tid < 256) { const f32x4* pp = (const f32x4*)(E.partr + (size_t)(tu.pm * BM + tid) * 16); const f32x4 p0 = pp[0], p1 = pp[1], p2 = pp[2], p3 = pp[3];
;                 const f32x4 ps = (p0 + p1) + (p2 + p3); tab[i * 512 + tid] = rsq(((ps[0] + ps[1]) + (ps[2] + ps[3])) * (1.f / DM) + EPS); }
;             else { const int mr = (tu.pm * BM < MX) ? ((tu.pm * BM) >> 11) : 8; tab[i * 512 + tid] = E.bias[(size_t)mr * E.bias_ld + tu.pn * BM + (tid - 256)]; }
;         }
.Ltab1_n1:
	s_add_u32 s10, s10, s60
	s_addc_u32 s11, s11, s78
	s_add_i32 s22, s22, 1
	v_cmp_gt_i64_e32 vcc, s[10:11], v[194:195]
	s_nop 1
	s_cbranch_vccnz .Ltab1_wait
	s_ashr_i32 s5, s10, 31
	s_lshr_b32 s5, s5, 29
	s_add_i32 s5, s10, s5
	s_ashr_i32 s12, s5, 3
	s_and_b32 s5, s5, -8
	s_sub_i32 s5, s10, s5
	s_cmp_lt_i32 s5, 0
	s_movk_i32 s13, 0x12a
	s_cselect_b32 s13, s13, 0x129
	s_mul_i32 s5, s5, s13
	s_add_i32 s5, s5, s12
	s_mul_hi_i32 s12, s5, 0x3e0f83e1
	s_lshr_b32 s13, s12, 31
	s_ashr_i32 s12, s12, 6
	s_add_i32 s12, s12, s13
	s_lshl_b32 s13, s12, 3
	s_sub_i32 s15, 0x48, s13
	s_min_i32 s16, s15, 8
	s_abs_i32 s15, s16
	v_cvt_f32_u32_e32 v1, s15
	s_sub_i32 s18, 0, s15
	s_mulk_i32 s12, 0x108
	s_sub_i32 s5, s5, s12
	v_rcp_iflag_f32_e32 v1, v1
	s_abs_i32 s12, s5
	s_xor_b32 s17, s5, s16
	s_ashr_i32 s17, s17, 31
	v_mul_f32_e32 v1, 0x4f7ffffe, v1
	v_cvt_u32_f32_e32 v1, v1
	s_nop 0
	v_readfirstlane_b32 s19, v1
	s_mul_i32 s18, s18, s19
	s_mul_hi_u32 s18, s19, s18
	s_add_i32 s19, s19, s18
	s_mul_hi_u32 s18, s12, s19
	s_mul_i32 s19, s18, s15
	s_sub_i32 s12, s12, s19
	s_add_i32 s20, s18, 1
	s_sub_i32 s19, s12, s15
	s_cmp_ge_u32 s12, s15
	s_cselect_b32 s18, s20, s18
	s_cselect_b32 s12, s19, s12
	s_add_i32 s19, s18, 1
	s_cmp_ge_u32 s12, s15
	s_cselect_b32 s12, s19, s18
	s_xor_b32 s12, s12, s17
	s_sub_i32 s15, s12, s17
	s_mul_i32 s12, s15, s16
	s_sub_i32 s5, s5, s12
	s_add_i32 s5, s13, s5
	s_and_b64 vcc, exec, s[2:3]
	s_cbranch_vccz .Ltab1_r2
	s_min_i32 s16, s5, 64
	s_ashr_i32 s18, s16, 3
	s_lshl_b32 s16, s15, 8
	s_ashr_i32 s17, s16, 31
	s_mul_hi_i32 s15, s18, 0x8400
	s_mul_i32 s18, s18, 0x8400
	s_add_u32 s18, s0, s18
	s_addc_u32 s15, s1, s15
	s_lshl_b64 s[16:17], s[16:17], 2
	s_add_u32 s16, s18, s16
	s_addc_u32 s17, s15, s17
	v_lshl_add_u64 v[2:3], v[192:193], 2, s[16:17]
	v_add_co_u32_e32 v2, vcc, 0x317f000, v2
	s_nop 1
	v_addc_co_u32_e32 v3, vcc, 0, v3, vcc
	global_load_dword v48, v[2:3], off offset:3072
	s_branch .Ltab1_n2
.Ltab1_r2:
	v_lshl_add_u32 v2, s5, 8, v192
	v_ashrrev_i32_e32 v3, 31, v2
	v_lshlrev_b64 v[2:3], 6, v[2:3]
	v_lshl_add_u64 v[6:7], s[8:9], 0, v[2:3]
	global_load_dwordx4 v[48:51], v[6:7], off
	global_load_dwordx4 v[52:55], v[6:7], off offset:16
	global_load_dwordx4 v[56:59], v[6:7], off offset:32
	global_load_dwordx4 v[60:63], v[6:7], off offset:48
.Ltab1_n2:
	s_add_u32 s10, s10, s60
	s_addc_u32 s11, s11, s78
	s_add_i32 s22, s22, 1
	v_cmp_gt_i64_e32 vcc, s[10:11], v[194:195]
	s_nop 1
	s_cbranch_vccnz .Ltab1_wait
	s_ashr_i32 s5, s10, 31
	s_lshr_b32 s5, s5, 29
	s_add_i32 s5, s10, s5
	s_ashr_i32 s12, s5, 3
	s_and_b32 s5, s5, -8
	s_sub_i32 s5, s10, s5
	s_cmp_lt_i32 s5, 0
	s_movk_i32 s13, 0x12a
	s_cselect_b32 s13, s13, 0x129
	s_mul_i32 s5, s5, s13
	s_add_i32 s5, s5, s12
	s_mul_hi_i32 s12, s5, 0x3e0f83e1
	s_lshr_b32 s13, s12, 31
	s_ashr_i32 s12, s12, 6
	s_add_i32 s12, s12, s13
	s_lshl_b32 s13, s12, 3
	s_sub_i32 s15, 0x48, s13
	s_min_i32 s16, s15, 8
	s_abs_i32 s15, s16
	v_cvt_f32_u32_e32 v1, s15
	s_sub_i32 s18, 0, s15
	s_mulk_i32 s12, 0x108
	s_sub_i32 s5, s5, s12
	v_rcp_iflag_f32_e32 v1, v1
	s_abs_i32 s12, s5
	s_xor_b32 s17, s5, s16
	s_ashr_i32 s17, s17, 31
	v_mul_f32_e32 v1, 0x4f7ffffe, v1
	v_cvt_u32_f32_e32 v1, v1
	s_nop 0
	v_readfirstlane_b32 s19, v1
	s_mul_i32 s18, s18, s19
	s_mul_hi_u32 s18, s19, s18
	s_add_i32 s19, s19, s18
	s_mul_hi_u32 s18, s12, s19
	s_mul_i32 s19, s18, s15
	s_sub_i32 s12, s12, s19
	s_add_i32 s20, s18, 1
	s_sub_i32 s19, s12, s15
	s_cmp_ge_u32 s12, s15
	s_cselect_b32 s18, s20, s18
	s_cselect_b32 s12, s19, s12
	s_add_i32 s19, s18, 1
	s_cmp_ge_u32 s12, s15
	s_cselect_b32 s12, s19, s18
	s_xor_b32 s12, s12, s17
	s_sub_i32 s15, s12, s17
	s_mul_i32 s12, s15, s16
	s_sub_i32 s5, s5, s12
	s_add_i32 s5, s13, s5
	s_and_b64 vcc, exec, s[2:3]
	s_cbranch_vccz .Ltab1_r3
	s_min_i32 s16, s5, 64
	s_ashr_i32 s18, s16, 3
	s_lshl_b32 s16, s15, 8
	s_ashr_i32 s17, s16, 31
	s_mul_hi_i32 s15, s18, 0x8400
	s_mul_i32 s18, s18, 0x8400
	s_add_u32 s18, s0, s18
	s_addc_u32 s15, s1, s15
	s_lshl_b64 s[16:17], s[16:17], 2
	s_add_u32 s16, s18, s16
	s_addc_u32 s17, s15, s17
	v_lshl_add_u64 v[2:3], v[192:193], 2, s[16:17]
	v_add_co_u32_e32 v2, vcc, 0x317f000, v2
	s_nop 1
	v_addc_co_u32_e32 v3, vcc, 0, v3, vcc
	global_load_dword v64, v[2:3], off offset:3072
	s_branch .Ltab1_n3
.Ltab1_r3:
	v_lshl_add_u32 v2, s5, 8, v192
	v_ashrrev_i32_e32 v3, 31, v2
	v_lshlrev_b64 v[2:3], 6, v[2:3]
	v_lshl_add_u64 v[6:7], s[8:9], 0, v[2:3]
	global_load_dwordx4 v[64:67], v[6:7], off
	global_load_dwordx4 v[68:71], v[6:7], off offset:16
	global_load_dwordx4 v[72:75], v[6:7], off offset:32
	global_load_dwordx4 v[76:79], v[6:7], off offset:48
.Ltab1_n3:
	s_add_u32 s10, s10, s60
	s_addc_u32 s11, s11, s78
	s_add_i32 s22, s22, 1
	v_cmp_gt_i64_e32 vcc, s[10:11], v[194:195]
	s_nop 1
	s_cbranch_vccnz .Ltab1_wait
	s_ashr_i32 s5, s10, 31
	s_lshr_b32 s5, s5, 29
	s_add_i32 s5, s10, s5
	s_ashr_i32 s12, s5, 3
	s_and_b32 s5, s5, -8
	s_sub_i32 s5, s10, s5
	s_cmp_lt_i32 s5, 0
	s_movk_i32 s13, 0x12a
	s_cselect_b32 s13, s13, 0x129
	s_mul_i32 s5, s5, s13
	s_add_i32 s5, s5, s12
	s_mul_hi_i32 s12, s5, 0x3e0f83e1
	s_lshr_b32 s13, s12, 31
	s_ashr_i32 s12, s12, 6
	s_add_i32 s12, s12, s13
	s_lshl_b32 s13, s12, 3
	s_sub_i32 s15, 0x48, s13
	s_min_i32 s16, s15, 8
	s_abs_i32 s15, s16
	v_cvt_f32_u32_e32 v1, s15
	s_sub_i32 s18, 0, s15
	s_mulk_i32 s12, 0x108
	s_sub_i32 s5, s5, s12
	v_rcp_iflag_f32_e32 v1, v1
	s_abs_i32 s12, s5
	s_xor_b32 s17, s5, s16
	s_ashr_i32 s17, s17, 31
	v_mul_f32_e32 v1, 0x4f7ffffe, v1
	v_cvt_u32_f32_e32 v1, v1
	s_nop 0
	v_readfirstlane_b32 s19, v1
	s_mul_i32 s18, s18, s19
	s_mul_hi_u32 s18, s19, s18
	s_add_i32 s19, s19, s18
	s_mul_hi_u32 s18, s12, s19
	s_mul_i32 s19, s18, s15
	s_sub_i32 s12, s12, s19
	s_add_i32 s20, s18, 1
	s_sub_i32 s19, s12, s15
	s_cmp_ge_u32 s12, s15
	s_cselect_b32 s18, s20, s18
	s_cselect_b32 s12, s19, s12
	s_add_i32 s19, s18, 1
	s_cmp_ge_u32 s12, s15
	s_cselect_b32 s12, s19, s18
	s_xor_b32 s12, s12, s17
	s_sub_i32 s15, s12, s17
	s_mul_i32 s12, s15, s16
	s_sub_i32 s5, s5, s12
	s_add_i32 s5, s13, s5
	s_and_b64 vcc, exec, s[2:3]
	s_cbranch_vccz .Ltab1_r4
	s_min_i32 s16, s5, 64
	s_ashr_i32 s18, s16, 3
	s_lshl_b32 s16, s15, 8
	s_ashr_i32 s17, s16, 31
	s_mul_hi_i32 s15, s18, 0x8400
	s_mul_i32 s18, s18, 0x8400
	s_add_u32 s18, s0, s18
	s_addc_u32 s15, s1, s15
	s_lshl_b64 s[16:17], s[16:17], 2
	s_add_u32 s16, s18, s16
	s_addc_u32 s17, s15, s17
	v_lshl_add_u64 v[2:3], v[192:193], 2, s[16:17]
	v_add_co_u32_e32 v2, vcc, 0x317f000, v2
	s_nop 1
	v_addc_co_u32_e32 v3, vcc, 0, v3, vcc
	global_load_dword v80, v[2:3], off offset:3072
	s_branch .Ltab1_n4
; __device__ __forceinline__ float rsq(float x) { return __builtin_amdgcn_rsqf(x); }
;     __device__ bool next(int i, Unit& u) const {
;         const long L = (long)i * G + c; if (L >= nwg) return false;
;         int wgid = (int)L; { const int q = nwg / NXCD, r = nwg % NXCD, xcd = wgid % NXCD, off = wgid / NXCD; wgid = (xcd < r ? xcd * (q + 1) : r * (q + 1) + (xcd - r) * q) + off; }
;         const int nig = WGM * nN, gid = wgid / nig, fm = gid * WGM, gsz = (nM - fm) < WGM ? (nM - fm) : WGM;
;         u.pm = fm + ((wgid % nig) % gsz); u.pn = (wgid % nig) / gsz; return true;
;     }
; template <class EpiT, class Sched>
; __device__ __forceinline__ void gemm_phase(LAS unsigned char* lds, const Gemm g, const Sched& S, const EpiT& E, int wv) {
;     ...
;     if constexpr (EpiT::TAB) {
;         Unit tu;
;         for (int i = 0; S.next(i, tu); ++i) {
;             if (tid < 256) { const f32x4* pp = (const f32x4*)(E.partr + (size_t)(tu.pm * BM + tid) * 16); const f32x4 p0 = pp[0], p1 = pp[1], p2 = pp[2], p3 = pp[3];
;                 const f32x4 ps = (p0 + p1) + (p2 + p3); tab[i * 512 + tid] = rsq(((ps[0] + ps[1]) + (ps[2] + ps[3])) * (1.f / DM) + EPS); }
;             else { const int mr = (tu.pm * BM < MX) ? ((tu.pm * BM) >> 11) : 8; tab[i * 512 + tid] = E.bias[(size_t)mr * E.bias_ld + tu.pn * BM + (tid - 256)]; }
;         }
.Ltab1_r4:
	v_lshl_add_u32 v2, s5, 8, v192
	v_ashrrev_i32_e32 v3, 31, v2
	v_lshlrev_b64 v[2:3], 6, v[2:3]
	v_lshl_add_u64 v[6:7], s[8:9], 0, v[2:3]
	global_load_dwordx4 v[80:83], v[6:7], off
	global_load_dwordx4 v[84:87], v[6:7], off offset:16
	global_load_dwordx4 v[88:91], v[6:7], off offset:32
	global_load_dwordx4 v[92:95], v[6:7], off offset:48
.Ltab1_n4:
	s_add_u32 s10, s10, s60
	s_addc_u32 s11, s11, s78
	s_add_i32 s22, s22, 1
	v_cmp_gt_i64_e32 vcc, s[10:11], v[194:195]
	s_nop 1
	s_cbranch_vccnz .Ltab1_wait
	s_ashr_i32 s5, s10, 31
	s_lshr_b32 s5, s5, 29
	s_add_i32 s5, s10, s5
	s_ashr_i32 s12, s5, 3
	s_and_b32 s5, s5, -8
	s_sub_i32 s5, s10, s5
	s_cmp_lt_i32 s5, 0
	s_movk_i32 s13, 0x12a
	s_cselect_b32 s13, s13, 0x129
	s_mul_i32 s5, s5, s13
	s_add_i32 s5, s5, s12
	s_mul_hi_i32 s12, s5, 0x3e0f83e1
	s_lshr_b32 s13, s12, 31
	s_ashr_i32 s12, s12, 6
	s_add_i32 s12, s12, s13
	s_lshl_b32 s13, s12, 3
	s_sub_i32 s15, 0x48, s13
	s_min_i32 s16, s15, 8
	s_abs_i32 s15, s16
	v_cvt_f32_u32_e32 v1, s15
	s_sub_i32 s18, 0, s15
	s_mulk_i32 s12, 0x108
	s_sub_i32 s5, s5, s12
	v_rcp_iflag_f32_e32 v1, v1
	s_abs_i32 s12, s5
	s_xor_b32 s17, s5, s16
	s_ashr_i32 s17, s17, 31
	v_mul_f32_e32 v1, 0x4f7ffffe, v1
	v_cvt_u32_f32_e32 v1, v1
	s_nop 0
	v_readfirstlane_b32 s19, v1
	s_mul_i32 s18, s18, s19
	s_mul_hi_u32 s18, s19, s18
	s_add_i32 s19, s19, s18
	s_mul_hi_u32 s18, s12, s19
	s_mul_i32 s19, s18, s15
	s_sub_i32 s12, s12, s19
	s_add_i32 s20, s18, 1
	s_sub_i32 s19, s12, s15
	s_cmp_ge_u32 s12, s15
	s_cselect_b32 s18, s20, s18
	s_cselect_b32 s12, s19, s12
	s_add_i32 s19, s18, 1
	s_cmp_ge_u32 s12, s15
	s_cselect_b32 s12, s19, s18
	s_xor_b32 s12, s12, s17
	s_sub_i32 s15, s12, s17
	s_mul_i32 s12, s15, s16
	s_sub_i32 s5, s5, s12
	s_add_i32 s5, s13, s5
	s_and_b64 vcc, exec, s[2:3]
	s_cbranch_vccz .Ltab1_r5
	s_min_i32 s16, s5, 64
	s_ashr_i32 s18, s16, 3
	s_lshl_b32 s16, s15, 8
	s_ashr_i32 s17, s16, 31
	s_mul_hi_i32 s15, s18, 0x8400
	s_mul_i32 s18, s18, 0x8400
	s_add_u32 s18, s0, s18
	s_addc_u32 s15, s1, s15
	s_lshl_b64 s[16:17], s[16:17], 2
	s_add_u32 s16, s18, s16
	s_addc_u32 s17, s15, s17
	v_lshl_add_u64 v[2:3], v[192:193], 2, s[16:17]
	v_add_co_u32_e32 v2, vcc, 0x317f000, v2
	s_nop 1
	v_addc_co_u32_e32 v3, vcc, 0, v3, vcc
	global_load_dword v96, v[2:3], off offset:3072
	s_branch .Ltab1_n5
.Ltab1_r5:
	v_lshl_add_u32 v2, s5, 8, v192
	v_ashrrev_i32_e32 v3, 31, v2
	v_lshlrev_b64 v[2:3], 6, v[2:3]
	v_lshl_add_u64 v[6:7], s[8:9], 0, v[2:3]
	global_load_dwordx4 v[96:99], v[6:7], off
	global_load_dwordx4 v[100:103], v[6:7], off offset:16
	global_load_dwordx4 v[104:107], v[6:7], off offset:32
	global_load_dwordx4 v[108:111], v[6:7], off offset:48
.Ltab1_n5:
	s_add_u32 s10, s10, s60
	s_addc_u32 s11, s11, s78
	s_add_i32 s22, s22, 1
	v_cmp_gt_i64_e32 vcc, s[10:11], v[194:195]
	s_nop 1
	s_cbranch_vccnz .Ltab1_wait
	s_ashr_i32 s5, s10, 31
	s_lshr_b32 s5, s5, 29
	s_add_i32 s5, s10, s5
	s_ashr_i32 s12, s5, 3
	s_and_b32 s5, s5, -8
	s_sub_i32 s5, s10, s5
	s_cmp_lt_i32 s5, 0
	s_movk_i32 s13, 0x12a
	s_cselect_b32 s13, s13, 0x129
	s_mul_i32 s5, s5, s13
	s_add_i32 s5, s5, s12
	s_mul_hi_i32 s12, s5, 0x3e0f83e1
	s_lshr_b32 s13, s12, 31
	s_ashr_i32 s12, s12, 6
	s_add_i32 s12, s12, s13
	s_lshl_b32 s13, s12, 3
	s_sub_i32 s15, 0x48, s13
	s_min_i32 s16, s15, 8
	s_abs_i32 s15, s16
	v_cvt_f32_u32_e32 v1, s15
	s_sub_i32 s18, 0, s15
	s_mulk_i32 s12, 0x108
	s_sub_i32 s5, s5, s12
	v_rcp_iflag_f32_e32 v1, v1
	s_abs_i32 s12, s5
	s_xor_b32 s17, s5, s16
	s_ashr_i32 s17, s17, 31
	v_mul_f32_e32 v1, 0x4f7ffffe, v1
	v_cvt_u32_f32_e32 v1, v1
	s_nop 0
	v_readfirstlane_b32 s19, v1
	s_mul_i32 s18, s18, s19
	s_mul_hi_u32 s18, s19, s18
	s_add_i32 s19, s19, s18
	s_mul_hi_u32 s18, s12, s19
	s_mul_i32 s19, s18, s15
	s_sub_i32 s12, s12, s19
	s_add_i32 s20, s18, 1
	s_sub_i32 s19, s12, s15
	s_cmp_ge_u32 s12, s15
	s_cselect_b32 s18, s20, s18
	s_cselect_b32 s12, s19, s12
	s_add_i32 s19, s18, 1
	s_cmp_ge_u32 s12, s15
	s_cselect_b32 s12, s19, s18
	s_xor_b32 s12, s12, s17
	s_sub_i32 s15, s12, s17
	s_mul_i32 s12, s15, s16
	s_sub_i32 s5, s5, s12
	s_add_i32 s5, s13, s5
	s_and_b64 vcc, exec, s[2:3]
	s_cbranch_vccz .Ltab1_r6
	s_min_i32 s16, s5, 64
	s_ashr_i32 s18, s16, 3
	s_lshl_b32 s16, s15, 8
	s_ashr_i32 s17, s16, 31
	s_mul_hi_i32 s15, s18, 0x8400
	s_mul_i32 s18, s18, 0x8400
	s_add_u32 s18, s0, s18
	s_addc_u32 s15, s1, s15
	s_lshl_b64 s[16:17], s[16:17], 2
	s_add_u32 s16, s18, s16
	s_addc_u32 s17, s15, s17
	v_lshl_add_u64 v[2:3], v[192:193], 2, s[16:17]
	v_add_co_u32_e32 v2, vcc, 0x317f000, v2
	s_nop 1
	v_addc_co_u32_e32 v3, vcc, 0, v3, vcc
	global_load_dword v112, v[2:3], off offset:3072
	s_branch .Ltab1_n6
.Ltab1_r6:
	v_lshl_add_u32 v2, s5, 8, v192
	v_ashrrev_i32_e32 v3, 31, v2
	v_lshlrev_b64 v[2:3], 6, v[2:3]
	v_lshl_add_u64 v[6:7], s[8:9], 0, v[2:3]
	global_load_dwordx4 v[112:115], v[6:7], off
	global_load_dwordx4 v[116:119], v[6:7], off offset:16
	global_load_dwordx4 v[120:123], v[6:7], off offset:32
	global_load_dwordx4 v[124:127], v[6:7], off offset:48
; __device__ __forceinline__ float rsq(float x) { return __builtin_amdgcn_rsqf(x); }
;     __device__ bool next(int i, Unit& u) const {
;         const long L = (long)i * G + c; if (L >= nwg) return false;
;         int wgid = (int)L; { const int q = nwg / NXCD, r = nwg % NXCD, xcd = wgid % NXCD, off = wgid / NXCD; wgid = (xcd < r ? xcd * (q + 1) : r * (q + 1) + (xcd - r) * q) + off; }
;         const int nig = WGM * nN, gid = wgid / nig, fm = gid * WGM, gsz = (nM - fm) < WGM ? (nM - fm) : WGM;
;         u.pm = fm + ((wgid % nig) % gsz); u.pn = (wgid % nig) / gsz; return true;
;     }
; template <class EpiT, class Sched>
; __device__ __forceinline__ void gemm_phase(LAS unsigned char* lds, const Gemm g, const Sched& S, const EpiT& E, int wv) {
;     ...
;     if constexpr (EpiT::TAB) {
;         Unit tu;
;         for (int i = 0; S.next(i, tu); ++i) {
;             if (tid < 256) { const f32x4* pp = (const f32x4*)(E.partr + (size_t)(tu.pm * BM + tid) * 16); const f32x4 p0 = pp[0], p1 = pp[1], p2 = pp[2], p3 = pp[3];
;                 const f32x4 ps = (p0 + p1) + (p2 + p3); tab[i * 512 + tid] = rsq(((ps[0] + ps[1]) + (ps[2] + ps[3])) * (1.f / DM) + EPS); }
;             else { const int mr = (tu.pm * BM < MX) ? ((tu.pm * BM) >> 11) : 8; tab[i * 512 + tid] = E.bias[(size_t)mr * E.bias_ld + tu.pn * BM + (tid - 256)]; }
;         }
.Ltab1_n6:
	s_add_u32 s10, s10, s60
	s_addc_u32 s11, s11, s78
	s_add_i32 s22, s22, 1
	v_cmp_gt_i64_e32 vcc, s[10:11], v[194:195]
	s_nop 1
	s_cbranch_vccnz .Ltab1_wait
	s_ashr_i32 s5, s10, 31
	s_lshr_b32 s5, s5, 29
	s_add_i32 s5, s10, s5
	s_ashr_i32 s12, s5, 3
	s_and_b32 s5, s5, -8
	s_sub_i32 s5, s10, s5
	s_cmp_lt_i32 s5, 0
	s_movk_i32 s13, 0x12a
	s_cselect_b32 s13, s13, 0x129
	s_mul_i32 s5, s5, s13
	s_add_i32 s5, s5, s12
	s_mul_hi_i32 s12, s5, 0x3e0f83e1
	s_lshr_b32 s13, s12, 31
	s_ashr_i32 s12, s12, 6
	s_add_i32 s12, s12, s13
	s_lshl_b32 s13, s12, 3
	s_sub_i32 s15, 0x48, s13
	s_min_i32 s16, s15, 8
	s_abs_i32 s15, s16
	v_cvt_f32_u32_e32 v1, s15
	s_sub_i32 s18, 0, s15
	s_mulk_i32 s12, 0x108
	s_sub_i32 s5, s5, s12
	v_rcp_iflag_f32_e32 v1, v1
	s_abs_i32 s12, s5
	s_xor_b32 s17, s5, s16
	s_ashr_i32 s17, s17, 31
	v_mul_f32_e32 v1, 0x4f7ffffe, v1
	v_cvt_u32_f32_e32 v1, v1
	s_nop 0
	v_readfirstlane_b32 s19, v1
	s_mul_i32 s18, s18, s19
	s_mul_hi_u32 s18, s19, s18
	s_add_i32 s19, s19, s18
	s_mul_hi_u32 s18, s12, s19
	s_mul_i32 s19, s18, s15
	s_sub_i32 s12, s12, s19
	s_add_i32 s20, s18, 1
	s_sub_i32 s19, s12, s15
	s_cmp_ge_u32 s12, s15
	s_cselect_b32 s18, s20, s18
	s_cselect_b32 s12, s19, s12
	s_add_i32 s19, s18, 1
	s_cmp_ge_u32 s12, s15
	s_cselect_b32 s12, s19, s18
	s_xor_b32 s12, s12, s17
	s_sub_i32 s15, s12, s17
	s_mul_i32 s12, s15, s16
	s_sub_i32 s5, s5, s12
	s_add_i32 s5, s13, s5
	s_and_b64 vcc, exec, s[2:3]
	s_cbranch_vccz .Ltab1_r7
	s_min_i32 s16, s5, 64
	s_ashr_i32 s18, s16, 3
	s_lshl_b32 s16, s15, 8
	s_ashr_i32 s17, s16, 31
	s_mul_hi_i32 s15, s18, 0x8400
	s_mul_i32 s18, s18, 0x8400
	s_add_u32 s18, s0, s18
	s_addc_u32 s15, s1, s15
	s_lshl_b64 s[16:17], s[16:17], 2
	s_add_u32 s16, s18, s16
	s_addc_u32 s17, s15, s17
	v_lshl_add_u64 v[2:3], v[192:193], 2, s[16:17]
	v_add_co_u32_e32 v2, vcc, 0x317f000, v2
	s_nop 1
	v_addc_co_u32_e32 v3, vcc, 0, v3, vcc
	global_load_dword v128, v[2:3], off offset:3072
	s_branch .Ltab1_n7
.Ltab1_r7:
	v_lshl_add_u32 v2, s5, 8, v192
	v_ashrrev_i32_e32 v3, 31, v2
	v_lshlrev_b64 v[2:3], 6, v[2:3]
	v_lshl_add_u64 v[6:7], s[8:9], 0, v[2:3]
	global_load_dwordx4 v[128:131], v[6:7], off
	global_load_dwordx4 v[132:135], v[6:7], off offset:16
	global_load_dwordx4 v[136:139], v[6:7], off offset:32
	global_load_dwordx4 v[140:143], v[6:7], off offset:48
.Ltab1_n7:
	s_add_u32 s10, s10, s60
	s_addc_u32 s11, s11, s78
	s_add_i32 s22, s22, 1
	v_cmp_gt_i64_e32 vcc, s[10:11], v[194:195]
	s_nop 1
	s_cbranch_vccnz .Ltab1_wait
	s_ashr_i32 s5, s10, 31
	s_lshr_b32 s5, s5, 29
	s_add_i32 s5, s10, s5
	s_ashr_i32 s12, s5, 3
	s_and_b32 s5, s5, -8
	s_sub_i32 s5, s10, s5
	s_cmp_lt_i32 s5, 0
	s_movk_i32 s13, 0x12a
	s_cselect_b32 s13, s13, 0x129
	s_mul_i32 s5, s5, s13
	s_add_i32 s5, s5, s12
	s_mul_hi_i32 s12, s5, 0x3e0f83e1
	s_lshr_b32 s13, s12, 31
	s_ashr_i32 s12, s12, 6
	s_add_i32 s12, s12, s13
	s_lshl_b32 s13, s12, 3
	s_sub_i32 s15, 0x48, s13
	s_min_i32 s16, s15, 8
	s_abs_i32 s15, s16
	v_cvt_f32_u32_e32 v1, s15
	s_sub_i32 s18, 0, s15
	s_mulk_i32 s12, 0x108
	s_sub_i32 s5, s5, s12
	v_rcp_iflag_f32_e32 v1, v1
	s_abs_i32 s12, s5
	s_xor_b32 s17, s5, s16
	s_ashr_i32 s17, s17, 31
	v_mul_f32_e32 v1, 0x4f7ffffe, v1
	v_cvt_u32_f32_e32 v1, v1
	s_nop 0
	v_readfirstlane_b32 s19, v1
	s_mul_i32 s18, s18, s19
	s_mul_hi_u32 s18, s19, s18
	s_add_i32 s19, s19, s18
	s_mul_hi_u32 s18, s12, s19
	s_mul_i32 s19, s18, s15
	s_sub_i32 s12, s12, s19
	s_add_i32 s20, s18, 1
	s_sub_i32 s19, s12, s15
	s_cmp_ge_u32 s12, s15
	s_cselect_b32 s18, s20, s18
	s_cselect_b32 s12, s19, s12
	s_add_i32 s19, s18, 1
	s_cmp_ge_u32 s12, s15
	s_cselect_b32 s12, s19, s18
	s_xor_b32 s12, s12, s17
	s_sub_i32 s15, s12, s17
	s_mul_i32 s12, s15, s16
	s_sub_i32 s5, s5, s12
	s_add_i32 s5, s13, s5
	s_and_b64 vcc, exec, s[2:3]
	s_cbranch_vccz .Ltab1_r8
	s_min_i32 s16, s5, 64
	s_ashr_i32 s18, s16, 3
	s_lshl_b32 s16, s15, 8
	s_ashr_i32 s17, s16, 31
	s_mul_hi_i32 s15, s18, 0x8400
	s_mul_i32 s18, s18, 0x8400
	s_add_u32 s18, s0, s18
	s_addc_u32 s15, s1, s15
	s_lshl_b64 s[16:17], s[16:17], 2
	s_add_u32 s16, s18, s16
	s_addc_u32 s17, s15, s17
	v_lshl_add_u64 v[2:3], v[192:193], 2, s[16:17]
	v_add_co_u32_e32 v2, vcc, 0x317f000, v2
	s_nop 1
	v_addc_co_u32_e32 v3, vcc, 0, v3, vcc
	global_load_dword v144, v[2:3], off offset:3072
	s_branch .Ltab1_n8
.Ltab1_r8:
	v_lshl_add_u32 v2, s5, 8, v192
	v_ashrrev_i32_e32 v3, 31, v2
	v_lshlrev_b64 v[2:3], 6, v[2:3]
	v_lshl_add_u64 v[6:7], s[8:9], 0, v[2:3]
	global_load_dwordx4 v[144:147], v[6:7], off
	global_load_dwordx4 v[148:151], v[6:7], off offset:16
	global_load_dwordx4 v[152:155], v[6:7], off offset:32
	global_load_dwordx4 v[156:159], v[6:7], off offset:48
.Ltab1_n8:
	s_add_u32 s10, s10, s60
	s_addc_u32 s11, s11, s78
	s_add_i32 s22, s22, 1
	v_cmp_gt_i64_e32 vcc, s[10:11], v[194:195]
	s_nop 1
	s_cbranch_vccnz .Ltab1_wait
	s_ashr_i32 s5, s10, 31
	s_lshr_b32 s5, s5, 29
	s_add_i32 s5, s10, s5
	s_ashr_i32 s12, s5, 3
	s_and_b32 s5, s5, -8
	s_sub_i32 s5, s10, s5
	s_cmp_lt_i32 s5, 0
	s_movk_i32 s13, 0x12a
	s_cselect_b32 s13, s13, 0x129
	s_mul_i32 s5, s5, s13
	s_add_i32 s5, s5, s12
	s_mul_hi_i32 s12, s5, 0x3e0f83e1
	s_lshr_b32 s13, s12, 31
	s_ashr_i32 s12, s12, 6
	s_add_i32 s12, s12, s13
	s_lshl_b32 s13, s12, 3
	s_sub_i32 s15, 0x48, s13
	s_min_i32 s16, s15, 8
	s_abs_i32 s15, s16
	v_cvt_f32_u32_e32 v1, s15
	s_sub_i32 s18, 0, s15
	s_mulk_i32 s12, 0x108
	s_sub_i32 s5, s5, s12
	v_rcp_iflag_f32_e32 v1, v1
	s_abs_i32 s12, s5
	s_xor_b32 s17, s5, s16
	s_ashr_i32 s17, s17, 31
	v_mul_f32_e32 v1, 0x4f7ffffe, v1
	v_cvt_u32_f32_e32 v1, v1
	s_nop 0
	v_readfirstlane_b32 s19, v1
	s_mul_i32 s18, s18, s19
	s_mul_hi_u32 s18, s19, s18
	s_add_i32 s19, s19, s18
	s_mul_hi_u32 s18, s12, s19
	s_mul_i32 s19, s18, s15
	s_sub_i32 s12, s12, s19
	s_add_i32 s20, s18, 1
	s_sub_i32 s19, s12, s15
	s_cmp_ge_u32 s12, s15
	s_cselect_b32 s18, s20, s18
	s_cselect_b32 s12, s19, s12
	s_add_i32 s19, s18, 1
	s_cmp_ge_u32 s12, s15
	s_cselect_b32 s12, s19, s18
	s_xor_b32 s12, s12, s17
	s_sub_i32 s15, s12, s17
	s_mul_i32 s12, s15, s16
	s_sub_i32 s5, s5, s12
	s_add_i32 s5, s13, s5
	s_and_b64 vcc, exec, s[2:3]
	s_cbranch_vccz .Ltab1_r9
	s_min_i32 s16, s5, 64
	s_ashr_i32 s18, s16, 3
	s_lshl_b32 s16, s15, 8
	s_ashr_i32 s17, s16, 31
	s_mul_hi_i32 s15, s18, 0x8400
	s_mul_i32 s18, s18, 0x8400
	s_add_u32 s18, s0, s18
	s_addc_u32 s15, s1, s15
	s_lshl_b64 s[16:17], s[16:17], 2
	s_add_u32 s16, s18, s16
	s_addc_u32 s17, s15, s17
	v_lshl_add_u64 v[2:3], v[192:193], 2, s[16:17]
	v_add_co_u32_e32 v2, vcc, 0x317f000, v2
	s_nop 1
	v_addc_co_u32_e32 v3, vcc, 0, v3, vcc
	global_load_dword v160, v[2:3], off offset:3072
	s_branch .Ltab1_n9
; __device__ __forceinline__ float rsq(float x) { return __builtin_amdgcn_rsqf(x); }
; template <class EpiT, class Sched>
; __device__ __forceinline__ void gemm_phase(LAS unsigned char* lds, const Gemm g, const Sched& S, const EpiT& E, int wv) {
;     ...
;     if constexpr (EpiT::TAB) {
;         Unit tu;
;         for (int i = 0; S.next(i, tu); ++i) {
;             if (tid < 256) { const f32x4* pp = (const f32x4*)(E.partr + (size_t)(tu.pm * BM + tid) * 16); const f32x4 p0 = pp[0], p1 = pp[1], p2 = pp[2], p3 = pp[3];
;                 const f32x4 ps = (p0 + p1) + (p2 + p3); tab[i * 512 + tid] = rsq(((ps[0] + ps[1]) + (ps[2] + ps[3])) * (1.f / DM) + EPS); }
;             else { const int mr = (tu.pm * BM < MX) ? ((tu.pm * BM) >> 11) : 8; tab[i * 512 + tid] = E.bias[(size_t)mr * E.bias_ld + tu.pn * BM + (tid - 256)]; }
;         }
;         __syncthreads();
.Ltab1_r9:
	v_lshl_add_u32 v2, s5, 8, v192
	v_ashrrev_i32_e32 v3, 31, v2
	v_lshlrev_b64 v[2:3], 6, v[2:3]
	v_lshl_add_u64 v[6:7], s[8:9], 0, v[2:3]
	global_load_dwordx4 v[160:163], v[6:7], off
	global_load_dwordx4 v[164:167], v[6:7], off offset:16
	global_load_dwordx4 v[168:171], v[6:7], off offset:32
	global_load_dwordx4 v[172:175], v[6:7], off offset:48
.Ltab1_n9:
	s_add_u32 s10, s10, s60
	s_addc_u32 s11, s11, s78
	s_add_i32 s22, s22, 1
.Ltab1_wait:
	s_waitcnt vmcnt(0)
	s_cmp_le_u32 s22, 0
	s_cbranch_scc1 .Ltab1_done
	s_and_b64 vcc, exec, s[2:3]
	s_cbranch_vccnz .Ltab1_w0
	v_pk_add_f32 v[18:19], v[18:19], v[22:23]
	v_pk_add_f32 v[16:17], v[16:17], v[20:21]
	v_pk_add_f32 v[6:7], v[26:27], v[30:31]
	v_pk_add_f32 v[10:11], v[24:25], v[28:29]
	v_pk_add_f32 v[18:19], v[18:19], v[6:7]
	v_pk_add_f32 v[16:17], v[16:17], v[10:11]
	s_nop 0
	v_pk_mov_b32 v[6:7], v[16:17], v[18:19] op_sel:[1,0]
	v_mov_b32_e32 v17, v19
	v_pk_add_f32 v[16:17], v[6:7], v[16:17]
	s_nop 0
	v_add_f32_e32 v1, v16, v17
	v_fmamk_f32 v1, v1, 0x3a800000, v225
	v_rsq_f32_e32 v16, v1
.Ltab1_w0:
	ds_write_b32 v0, v16
	v_add_u32_e32 v0, 0x800, v0
	s_cmp_le_u32 s22, 1
	s_cbranch_scc1 .Ltab1_done
	s_and_b64 vcc, exec, s[2:3]
	s_cbranch_vccnz .Ltab1_w1
	v_pk_add_f32 v[34:35], v[34:35], v[38:39]
	v_pk_add_f32 v[32:33], v[32:33], v[36:37]
	v_pk_add_f32 v[6:7], v[42:43], v[46:47]
	v_pk_add_f32 v[10:11], v[40:41], v[44:45]
	v_pk_add_f32 v[34:35], v[34:35], v[6:7]
	v_pk_add_f32 v[32:33], v[32:33], v[10:11]
	s_nop 0
	v_pk_mov_b32 v[6:7], v[32:33], v[34:35] op_sel:[1,0]
	v_mov_b32_e32 v33, v35
	v_pk_add_f32 v[32:33], v[6:7], v[32:33]
	s_nop 0
	v_add_f32_e32 v1, v32, v33
	v_fmamk_f32 v1, v1, 0x3a800000, v225
	v_rsq_f32_e32 v32, v1
.Ltab1_w1:
	ds_write_b32 v0, v32
	v_add_u32_e32 v0, 0x800, v0
	s_cmp_le_u32 s22, 2
	s_cbranch_scc1 .Ltab1_done
	s_and_b64 vcc, exec, s[2:3]
	s_cbranch_vccnz .Ltab1_w2
	v_pk_add_f32 v[50:51], v[50:51], v[54:55]
	v_pk_add_f32 v[48:49], v[48:49], v[52:53]
	v_pk_add_f32 v[6:7], v[58:59], v[62:63]
	v_pk_add_f32 v[10:11], v[56:57], v[60:61]
	v_pk_add_f32 v[50:51], v[50:51], v[6:7]
	v_pk_add_f32 v[48:49], v[48:49], v[10:11]
	s_nop 0
	v_pk_mov_b32 v[6:7], v[48:49], v[50:51] op_sel:[1,0]
	v_mov_b32_e32 v49, v51
	v_pk_add_f32 v[48:49], v[6:7], v[48:49]
	s_nop 0
	v_add_f32_e32 v1, v48, v49
	v_fmamk_f32 v1, v1, 0x3a800000, v225
	v_rsq_f32_e32 v48, v1
.Ltab1_w2:
	ds_write_b32 v0, v48
	v_add_u32_e32 v0, 0x800, v0
	s_cmp_le_u32 s22, 3
	s_cbranch_scc1 .Ltab1_done
	s_and_b64 vcc, exec, s[2:3]
	s_cbranch_vccnz .Ltab1_w3
	v_pk_add_f32 v[66:67], v[66:67], v[70:71]
	v_pk_add_f32 v[64:65], v[64:65], v[68:69]
	v_pk_add_f32 v[6:7], v[74:75], v[78:79]
	v_pk_add_f32 v[10:11], v[72:73], v[76:77]
	v_pk_add_f32 v[66:67], v[66:67], v[6:7]
	v_pk_add_f32 v[64:65], v[64:65], v[10:11]
	s_nop 0
	v_pk_mov_b32 v[6:7], v[64:65], v[66:67] op_sel:[1,0]
	v_mov_b32_e32 v65, v67
	v_pk_add_f32 v[64:65], v[6:7], v[64:65]
	s_nop 0
	v_add_f32_e32 v1, v64, v65
	v_fmamk_f32 v1, v1, 0x3a800000, v225
	v_rsq_f32_e32 v64, v1
.Ltab1_w3:
	ds_write_b32 v0, v64
	v_add_u32_e32 v0, 0x800, v0
	s_cmp_le_u32 s22, 4
	s_cbranch_scc1 .Ltab1_done
	s_and_b64 vcc, exec, s[2:3]
	s_cbranch_vccnz .Ltab1_w4
	v_pk_add_f32 v[82:83], v[82:83], v[86:87]
	v_pk_add_f32 v[80:81], v[80:81], v[84:85]
	v_pk_add_f32 v[6:7], v[90:91], v[94:95]
	v_pk_add_f32 v[10:11], v[88:89], v[92:93]
	v_pk_add_f32 v[82:83], v[82:83], v[6:7]
	v_pk_add_f32 v[80:81], v[80:81], v[10:11]
	s_nop 0
	v_pk_mov_b32 v[6:7], v[80:81], v[82:83] op_sel:[1,0]
	v_mov_b32_e32 v81, v83
	v_pk_add_f32 v[80:81], v[6:7], v[80:81]
	s_nop 0
	v_add_f32_e32 v1, v80, v81
	v_fmamk_f32 v1, v1, 0x3a800000, v225
	v_rsq_f32_e32 v80, v1
.Ltab1_w4:
	ds_write_b32 v0, v80
	v_add_u32_e32 v0, 0x800, v0
	s_cmp_le_u32 s22, 5
	s_cbranch_scc1 .Ltab1_done
	s_and_b64 vcc, exec, s[2:3]
	s_cbranch_vccnz .Ltab1_w5
	v_pk_add_f32 v[98:99], v[98:99], v[102:103]
	v_pk_add_f32 v[96:97], v[96:97], v[100:101]
	v_pk_add_f32 v[6:7], v[106:107], v[110:111]
	v_pk_add_f32 v[10:11], v[104:105], v[108:109]
	v_pk_add_f32 v[98:99], v[98:99], v[6:7]
	v_pk_add_f32 v[96:97], v[96:97], v[10:11]
	s_nop 0
	v_pk_mov_b32 v[6:7], v[96:97], v[98:99] op_sel:[1,0]
	v_mov_b32_e32 v97, v99
	v_pk_add_f32 v[96:97], v[6:7], v[96:97]
	s_nop 0
	v_add_f32_e32 v1, v96, v97
	v_fmamk_f32 v1, v1, 0x3a800000, v225
	v_rsq_f32_e32 v96, v1
.Ltab1_w5:
	ds_write_b32 v0, v96
	v_add_u32_e32 v0, 0x800, v0
	s_cmp_le_u32 s22, 6
	s_cbranch_scc1 .Ltab1_done
	s_and_b64 vcc, exec, s[2:3]
	s_cbranch_vccnz .Ltab1_w6
	v_pk_add_f32 v[114:115], v[114:115], v[118:119]
	v_pk_add_f32 v[112:113], v[112:113], v[116:117]
	v_pk_add_f32 v[6:7], v[122:123], v[126:127]
	v_pk_add_f32 v[10:11], v[120:121], v[124:125]
	v_pk_add_f32 v[114:115], v[114:115], v[6:7]
	v_pk_add_f32 v[112:113], v[112:113], v[10:11]
	s_nop 0
	v_pk_mov_b32 v[6:7], v[112:113], v[114:115] op_sel:[1,0]
	v_mov_b32_e32 v113, v115
	v_pk_add_f32 v[112:113], v[6:7], v[112:113]
	s_nop 0
	v_add_f32_e32 v1, v112, v113
	v_fmamk_f32 v1, v1, 0x3a800000, v225
	v_rsq_f32_e32 v112, v1
.Ltab1_w6:
	ds_write_b32 v0, v112
	v_add_u32_e32 v0, 0x800, v0
	s_cmp_le_u32 s22, 7
	s_cbranch_scc1 .Ltab1_done
	s_and_b64 vcc, exec, s[2:3]
	s_cbranch_vccnz .Ltab1_w7
	v_pk_add_f32 v[130:131], v[130:131], v[134:135]
	v_pk_add_f32 v[128:129], v[128:129], v[132:133]
	v_pk_add_f32 v[6:7], v[138:139], v[142:143]
	v_pk_add_f32 v[10:11], v[136:137], v[140:141]
	v_pk_add_f32 v[130:131], v[130:131], v[6:7]
	v_pk_add_f32 v[128:129], v[128:129], v[10:11]
	s_nop 0
	v_pk_mov_b32 v[6:7], v[128:129], v[130:131] op_sel:[1,0]
	v_mov_b32_e32 v129, v131
	v_pk_add_f32 v[128:129], v[6:7], v[128:129]
	s_nop 0
	v_add_f32_e32 v1, v128, v129
	v_fmamk_f32 v1, v1, 0x3a800000, v225
	v_rsq_f32_e32 v128, v1
; template <class EpiT, class Sched>
; __device__ __forceinline__ void gemm_phase(LAS unsigned char* lds, const Gemm g, const Sched& S, const EpiT& E, int wv) {
;     ...
;     for (int i = 0; i < 2; ++i) { int R, C; stage_rc(tid * 16 + i * 8192, R, C); const int Rb = EpiT::PERM ? ((R & ~31) + perm32(R & 31)) : R;
;         voffA[i] = (unsigned)(R * g.lda + C) * 2u; voffB[i] = (unsigned)(Rb * g.ldb + C) * 2u; }
;     const size_t kstep = (size_t)(BK * 2);
;     const size_t hstepA = (size_t)HALF * g.lda * 2, hstepB = (size_t)HALF * g.ldb * 2;
;     const size_t tstepA = 2 * hstepA, tstepB = 2 * hstepB;
;     const unsigned ldsw = (unsigned)wid * 1024u;
;     const int foff = lds_byte(fr, fq * 8);
;     const int aoff = wr * 8192 + foff, boff = wc * 4096 + foff;
;     ...
;     Unit cur, nxt; int ui = 0;
;     if (!S.next(0, cur)) return;
;     if constexpr (EpiT::TAB) {
;         Unit tu;
;         for (int i = 0; S.next(i, tu); ++i) {
;             if (tid < 256) { const f32x4* pp = (const f32x4*)(E.partr + (size_t)(tu.pm * BM + tid) * 16); const f32x4 p0 = pp[0], p1 = pp[1], p2 = pp[2], p3 = pp[3];
;                 const f32x4 ps = (p0 + p1) + (p2 + p3); tab[i * 512 + tid] = rsq(((ps[0] + ps[1]) + (ps[2] + ps[3])) * (1.f / DM) + EPS); }
;             else { const int mr = (tu.pm * BM < MX) ? ((tu.pm * BM) >> 11) : 8; tab[i * 512 + tid] = E.bias[(size_t)mr * E.bias_ld + tu.pn * BM + (tid - 256)]; }
;         }
;         __syncthreads();
;     }
;     f32x4 acc[2][2][4][2];
; #pragma unroll
;     for (int a = 0; a < 2; ++a)
; #pragma unroll
;         for (int b = 0; b < 2; ++b)
; #pragma unroll
;             for (int m = 0; m < 4; ++m)
; #pragma unroll
;                 for (int n = 0; n < 2; ++n) acc[a][b][m][n] = (f32x4){0.f, 0.f, 0.f, 0.f};
;     bf16x8 At[4][2], B0[2][2], B1[2][2];
;     const char* cA = (const char*)g.A + (size_t)cur.pm * tstepA + (size_t)(cur.pn >> g.zshift) * g.zA; const char* cB = (const char*)g.Bt + (size_t)cur.pn * tstepB;
;     PG8_STAGE(PG8_SB(0, 0), cB, voffB); PG8_STAGE(PG8_SB(0, 1), cB + hstepB, voffB); PG8_STAGE(PG8_SA(0, 0), cA, voffA); PG8_STAGE(PG8_SA(0, 1), cA + hstepA, voffA);
;     if (wr == 1) PG8_BAR;
;     PG8_WAIT_V(2); PG8_BAR;
;     PG8_STAGE(PG8_SB(1, 0), cB + kstep, voffB); PG8_STAGE(PG8_SA(1, 0), cA + kstep, voffA); PG8_STAGE(PG8_SB(1, 1), cB + hstepB + kstep, voffB);
;     PG8_WAIT_V(6); PG8_BAR;
.Ltab1_w7:
	ds_write_b32 v0, v128
	v_add_u32_e32 v0, 0x800, v0
	s_cmp_le_u32 s22, 8
	s_cbranch_scc1 .Ltab1_done
	s_and_b64 vcc, exec, s[2:3]
	s_cbranch_vccnz .Ltab1_w8
	v_pk_add_f32 v[146:147], v[146:147], v[150:151]
	v_pk_add_f32 v[144:145], v[144:145], v[148:149]
	v_pk_add_f32 v[6:7], v[154:155], v[158:159]
	v_pk_add_f32 v[10:11], v[152:153], v[156:157]
	v_pk_add_f32 v[146:147], v[146:147], v[6:7]
	v_pk_add_f32 v[144:145], v[144:145], v[10:11]
	s_nop 0
	v_pk_mov_b32 v[6:7], v[144:145], v[146:147] op_sel:[1,0]
	v_mov_b32_e32 v145, v147
	v_pk_add_f32 v[144:145], v[6:7], v[144:145]
	s_nop 0
	v_add_f32_e32 v1, v144, v145
	v_fmamk_f32 v1, v1, 0x3a800000, v225
	v_rsq_f32_e32 v144, v1
.Ltab1_w8:
	ds_write_b32 v0, v144
	v_add_u32_e32 v0, 0x800, v0
	s_cmp_le_u32 s22, 9
	s_cbranch_scc1 .Ltab1_done
	s_and_b64 vcc, exec, s[2:3]
	s_cbranch_vccnz .Ltab1_w9
	v_pk_add_f32 v[162:163], v[162:163], v[166:167]
	v_pk_add_f32 v[160:161], v[160:161], v[164:165]
	v_pk_add_f32 v[6:7], v[170:171], v[174:175]
	v_pk_add_f32 v[10:11], v[168:169], v[172:173]
	v_pk_add_f32 v[162:163], v[162:163], v[6:7]
	v_pk_add_f32 v[160:161], v[160:161], v[10:11]
	s_nop 0
	v_pk_mov_b32 v[6:7], v[160:161], v[162:163] op_sel:[1,0]
	v_mov_b32_e32 v161, v163
	v_pk_add_f32 v[160:161], v[6:7], v[160:161]
	s_nop 0
	v_add_f32_e32 v1, v160, v161
	v_fmamk_f32 v1, v1, 0x3a800000, v225
	v_rsq_f32_e32 v160, v1
.Ltab1_w9:
	ds_write_b32 v0, v160
	v_add_u32_e32 v0, 0x800, v0
.Ltab1_done:
.LBB0_238:
	v_ashrrev_i32_e32 v1, 31, v192
	v_lshrrev_b32_e32 v1, 26, v1
	v_add_u32_e32 v1, v192, v1
	v_ashrrev_i32_e32 v9, 6, v1
	v_bfe_i32 v1, v192, 27, 1
	v_lshlrev_b32_e32 v0, 4, v192
	v_lshrrev_b32_e32 v1, 22, v1
	v_add_u32_e32 v1, v0, v1
	v_and_b32_e32 v1, 0xfffffc00, v1
	v_sub_u32_e32 v1, v0, v1
	v_lshrrev_b32_e32 v2, 4, v1
	v_bitop3_b32 v1, v2, v1, 32 bitop3:0x6c
	v_ashrrev_i32_e32 v3, 31, v1
	v_lshrrev_b32_e32 v3, 26, v3
	v_add_u32_e32 v3, v1, v3
	v_lshlrev_b32_e32 v2, 3, v9
	v_ashrrev_i32_e32 v10, 6, v3
	v_and_b32_e32 v3, 0xc0, v3
	v_and_b32_e32 v2, -16, v2
	v_sub_u32_e32 v1, v1, v3
	v_add_u32_e32 v2, v10, v2
	v_ashrrev_i16_sdwa v1, v224, sext(v1) dst_sel:DWORD dst_unused:UNUSED_PAD src0_sel:DWORD src1_sel:BYTE_0
	v_lshlrev_b32_e32 v4, 5, v9
	v_bfe_i32 v11, v1, 0, 16
	v_lshlrev_b32_e32 v1, 1, v2
	v_lshrrev_b32_e32 v3, 2, v2
	v_and_b32_e32 v5, 3, v10
	s_mov_b32 s3, 0x1fffe0
	v_and_b32_e32 v4, 32, v4
	v_and_b32_e32 v1, 24, v1
	v_and_b32_e32 v3, 4, v3
	v_and_or_b32 v5, v2, s3, v5
	v_or3_b32 v1, v5, v3, v1
	v_add_lshl_u32 v3, v4, v11, 1
	v_add_u32_e32 v0, 0x2000, v0
	v_lshl_add_u32 v192, v1, 11, v3
	v_ashrrev_i32_e32 v1, 31, v0
	v_lshrrev_b32_e32 v1, 22, v1
	v_add_u32_e32 v1, v0, v1
	v_ashrrev_i32_e32 v12, 10, v1
	v_mul_i32_i24_e32 v1, 0x400, v12
	v_sub_u32_e32 v0, v0, v1
	v_lshrrev_b32_e32 v1, 4, v0
	v_bitop3_b32 v0, v1, v0, 32 bitop3:0x6c
	v_lshl_add_u32 v136, v2, 11, v3
	v_ashrrev_i32_e32 v2, 31, v0
	v_lshrrev_b32_e32 v2, 26, v2
	v_lshlrev_b32_e32 v1, 3, v12
	v_add_u32_e32 v2, v0, v2
	s_add_u32 s33, s0, 0x3c00000
	v_and_b32_e32 v1, -16, v1
	v_ashrrev_i32_e32 v13, 6, v2
	s_addc_u32 s34, s1, 0
	s_ashr_i32 s2, s14, 6
	v_add_u32_e32 v1, v13, v1
	v_and_b32_e32 v2, 0xc0, v2
	v_and_b32_e32 v4, 3, v13
	s_ashr_i32 s25, s24, 31
	s_ashr_i32 s5, s4, 31
	v_sub_u32_e32 v0, v0, v2
	v_and_or_b32 v4, v1, s3, v4
	s_ashr_i32 s3, s14, 8
	s_lshl_b32 s35, s2, 10
	s_lshl_b64 s[8:9], s[24:25], 19
	s_lshl_b64 s[10:11], s[4:5], 19
	v_ashrrev_i16_sdwa v0, v224, sext(v0) dst_sel:DWORD dst_unused:UNUSED_PAD src0_sel:DWORD src1_sel:BYTE_0
	s_add_u32 s28, s0, s10
	v_lshlrev_b32_e32 v3, 5, v12
	v_bfe_i32 v14, v0, 0, 16
	v_lshlrev_b32_e32 v0, 1, v1
	v_lshrrev_b32_e32 v2, 2, v1
	s_addc_u32 s29, s1, s11
	s_add_i32 s36, s35, 0
	v_and_b32_e32 v3, 32, v3
	v_and_b32_e32 v0, 24, v0
	v_and_b32_e32 v2, 4, v2
	s_add_i32 m0, s36, 0x10000
	v_or3_b32 v0, v4, v2, v0
	v_add_lshl_u32 v2, v3, v14, 1
	s_waitcnt lgkmcnt(0)
	s_barrier
	global_load_lds_dwordx4 v192, s[28:29]
	s_add_i32 m0, s36, 0x12000
	v_lshl_add_u32 v140, v0, 11, v2
	s_add_u32 s10, s28, 0x40000
	global_load_lds_dwordx4 v140, s[28:29]
	s_addc_u32 s11, s29, 0
	s_add_i32 m0, s36, 0x14000
	v_lshl_add_u32 v138, v1, 11, v2
	global_load_lds_dwordx4 v192, s[10:11]
	s_add_i32 m0, s36, 0x16000
	s_add_u32 s26, s33, s8
	s_addc_u32 s27, s34, s9
	s_add_i32 s37, s36, 0x2000
	global_load_lds_dwordx4 v140, s[10:11]
	s_mov_b32 m0, s36
	s_add_u32 s8, s26, 0x40000
	global_load_lds_dwordx4 v136, s[26:27]
	s_mov_b32 m0, s37
	s_addc_u32 s9, s27, 0
	s_add_i32 s38, s36, 0x4000
	global_load_lds_dwordx4 v138, s[26:27]
	s_mov_b32 m0, s38
	s_add_i32 s39, s36, 0x6000
	global_load_lds_dwordx4 v136, s[8:9]
	s_mov_b32 m0, s39
	s_cmp_eq_u32 s3, 1
	global_load_lds_dwordx4 v138, s[8:9]
	v_mov_b32_e32 v141, v193
	v_mov_b32_e32 v137, v193
	v_mov_b32_e32 v139, v193
	s_cselect_b64 s[8:9], -1, 0
	v_lshl_add_u64 v[6:7], s[28:29], 0, v[192:193]
	v_lshl_add_u64 v[4:5], s[28:29], 0, v[140:141]
	v_lshl_add_u64 v[2:3], s[26:27], 0, v[136:137]
	v_lshl_add_u64 v[0:1], s[26:27], 0, v[138:139]
	s_and_b64 vcc, exec, s[8:9]
	s_cbranch_vccz .LBB0_240
	s_barrier

; __device__ __forceinline__ float rsq(float x) { return __builtin_amdgcn_rsqf(x); }
; template <class EpiT, class Sched>
; __device__ __forceinline__ void gemm_phase(LAS unsigned char* lds, const Gemm g, const Sched& S, const EpiT& E, int wv) {
;     ...
;     if constexpr (EpiT::TAB) {
;         Unit tu;
;         for (int i = 0; S.next(i, tu); ++i) {
;             if (tid < 256) { const f32x4* pp = (const f32x4*)(E.partr + (size_t)(tu.pm * BM + tid) * 16); const f32x4 p0 = pp[0], p1 = pp[1], p2 = pp[2], p3 = pp[3];
;                 const f32x4 ps = (p0 + p1) + (p2 + p3); tab[i * 512 + tid] = rsq(((ps[0] + ps[1]) + (ps[2] + ps[3])) * (1.f / DM) + EPS); }
;             else { const int mr = (tu.pm * BM < MX) ? ((tu.pm * BM) >> 11) : 8; tab[i * 512 + tid] = E.bias[(size_t)mr * E.bias_ld + tu.pn * BM + (tid - 256)]; }
;         }
.LBB0_1254:
	s_or_b64 exec, exec, s[0:1]
	v_readlane_b32 s2, v255, 0
	v_readlane_b32 s3, v255, 1
	s_mov_b32 s0, s79
	s_waitcnt lgkmcnt(0)
	s_barrier
	v_mbcnt_lo_u32_b32 v8, -1, 0
	v_mbcnt_hi_u32_b32 v8, -1, v8
	s_movk_i32 s5, 0x400
	s_cmp_eq_u32 s90, 3
	s_cselect_b32 s4, 0, 32
	s_cselect_b32 s5, 0x300, s5
	s_cmp_lt_u32 s79, s4
	s_cselect_b32 s5, 0, s5
	s_add_i32 s36, s79, 1
	s_add_i32 s36, s36, s5
	s_mov_b32 s37, 0
	s_cmp_lt_i32 s0, s36
	v_or_b32_e32 v192, s67, v8
	s_nop 0
	v_readfirstlane_b32 s12, v192
	s_cbranch_scc0 .LBB0_1278
	s_load_dwordx2 s[6:7], s[2:3], 0xd8
	s_movk_i32 s1, 0xff
	v_cmp_lt_i32_e64 s[2:3], s1, v192
	v_readlane_b32 s8, v255, 22
	s_waitcnt lgkmcnt(0)
	s_add_u32 s4, s6, 0x1fa00000
	s_addc_u32 s5, s7, 0
	s_ashr_i32 s1, s0, 31
	v_lshl_add_u32 v0, v192, 2, s8
	s_mov_b64 s[8:9], s[0:1]
	s_mov_b32 s20, 0
	s_cmp_ge_i32 s8, s36
	s_cbranch_scc1 .Ltab8_wait
	s_and_b32 s15, s8, 0xff
	s_lshr_b32 s16, s8, 8
	s_movk_i32 s17, 0xe0
	s_cmp_eq_u32 s90, 3
	s_cselect_b32 s17, 0x100, s17
	s_mul_i32 s17, s16, s17
	s_add_i32 s17, s15, s17
	s_lshr_b32 s13, s17, 4
	s_and_b32 s14, s17, 15
	s_and_b64 vcc, exec, s[2:3]
	s_cbranch_vccz .Ltab8_r0
	s_min_i32 s15, s13, 64
	s_ashr_i32 s16, s15, 3
	s_ashr_i32 s17, s16, 31
	s_lshl_b32 s14, s14, 8
	s_ashr_i32 s15, s14, 31
	s_lshl_b64 s[16:17], s[16:17], 14
	s_add_u32 s16, s6, s16
	s_addc_u32 s17, s7, s17
	s_lshl_b64 s[14:15], s[14:15], 2
	s_add_u32 s14, s16, s14
	s_addc_u32 s15, s17, s15
	v_lshl_add_u64 v[2:3], v[192:193], 2, s[14:15]
	v_add_co_u32_e32 v2, vcc, 0x31cf000, v2
	s_nop 1
	v_addc_co_u32_e32 v3, vcc, 0, v3, vcc
	global_load_dword v16, v[2:3], off offset:3072
	s_branch .Ltab8_n0
.Ltab8_r0:
	v_lshl_add_u32 v2, s13, 8, v192
	v_ashrrev_i32_e32 v3, 31, v2
	v_lshlrev_b64 v[2:3], 6, v[2:3]
	v_lshl_add_u64 v[6:7], s[4:5], 0, v[2:3]
	global_load_dwordx4 v[16:19], v[6:7], off
	global_load_dwordx4 v[20:23], v[6:7], off offset:16
	global_load_dwordx4 v[24:27], v[6:7], off offset:32
	global_load_dwordx4 v[28:31], v[6:7], off offset:48
.Ltab8_n0:
	s_add_u32 s8, s8, s60
	s_addc_u32 s9, s9, s78
	s_add_i32 s20, s20, 1
	s_cmp_ge_i32 s8, s36
	s_cbranch_scc1 .Ltab8_wait
	s_and_b32 s15, s8, 0xff
	s_lshr_b32 s16, s8, 8
	s_movk_i32 s17, 0xe0
	s_cmp_eq_u32 s90, 3
	s_cselect_b32 s17, 0x100, s17
	s_mul_i32 s17, s16, s17
	s_add_i32 s17, s15, s17
	s_lshr_b32 s13, s17, 4
	s_and_b32 s14, s17, 15
	s_and_b64 vcc, exec, s[2:3]
	s_cbranch_vccz .Ltab8_r1
	s_min_i32 s15, s13, 64
	s_ashr_i32 s16, s15, 3
	s_ashr_i32 s17, s16, 31
	s_lshl_b32 s14, s14, 8
	s_ashr_i32 s15, s14, 31
	s_lshl_b64 s[16:17], s[16:17], 14
	s_add_u32 s16, s6, s16
	s_addc_u32 s17, s7, s17
	s_lshl_b64 s[14:15], s[14:15], 2
	s_add_u32 s14, s16, s14
	s_addc_u32 s15, s17, s15
	v_lshl_add_u64 v[2:3], v[192:193], 2, s[14:15]
	v_add_co_u32_e32 v2, vcc, 0x31cf000, v2
	s_nop 1
	v_addc_co_u32_e32 v3, vcc, 0, v3, vcc
	global_load_dword v32, v[2:3], off offset:3072
	s_branch .Ltab8_n1
.Ltab8_r1:
	v_lshl_add_u32 v2, s13, 8, v192
	v_ashrrev_i32_e32 v3, 31, v2
	v_lshlrev_b64 v[2:3], 6, v[2:3]
	v_lshl_add_u64 v[6:7], s[4:5], 0, v[2:3]
	global_load_dwordx4 v[32:35], v[6:7], off
	global_load_dwordx4 v[36:39], v[6:7], off offset:16
	global_load_dwordx4 v[40:43], v[6:7], off offset:32
	global_load_dwordx4 v[44:47], v[6:7], off offset:48
.Ltab8_n1:
	s_add_u32 s8, s8, s60
	s_addc_u32 s9, s9, s78
	s_add_i32 s20, s20, 1
	s_cmp_ge_i32 s8, s36
	s_cbranch_scc1 .Ltab8_wait
	s_and_b32 s15, s8, 0xff
	s_lshr_b32 s16, s8, 8
	s_movk_i32 s17, 0xe0
	s_cmp_eq_u32 s90, 3
	s_cselect_b32 s17, 0x100, s17
	s_mul_i32 s17, s16, s17
	s_add_i32 s17, s15, s17
	s_lshr_b32 s13, s17, 4
	s_and_b32 s14, s17, 15
	s_and_b64 vcc, exec, s[2:3]
	s_cbranch_vccz .Ltab8_r2
	s_min_i32 s15, s13, 64
	s_ashr_i32 s16, s15, 3
	s_ashr_i32 s17, s16, 31
	s_lshl_b32 s14, s14, 8
	s_ashr_i32 s15, s14, 31
	s_lshl_b64 s[16:17], s[16:17], 14
	s_add_u32 s16, s6, s16
	s_addc_u32 s17, s7, s17
	s_lshl_b64 s[14:15], s[14:15], 2
	s_add_u32 s14, s16, s14
	s_addc_u32 s15, s17, s15
	v_lshl_add_u64 v[2:3], v[192:193], 2, s[14:15]
	v_add_co_u32_e32 v2, vcc, 0x31cf000, v2
	s_nop 1
	v_addc_co_u32_e32 v3, vcc, 0, v3, vcc
	global_load_dword v48, v[2:3], off offset:3072
	s_branch .Ltab8_n2
.Ltab8_r2:
	v_lshl_add_u32 v2, s13, 8, v192
	v_ashrrev_i32_e32 v3, 31, v2
	v_lshlrev_b64 v[2:3], 6, v[2:3]
	v_lshl_add_u64 v[6:7], s[4:5], 0, v[2:3]
	global_load_dwordx4 v[48:51], v[6:7], off
	global_load_dwordx4 v[52:55], v[6:7], off offset:16
	global_load_dwordx4 v[56:59], v[6:7], off offset:32
	global_load_dwordx4 v[60:63], v[6:7], off offset:48
.Ltab8_n2:
	s_add_u32 s8, s8, s60
	s_addc_u32 s9, s9, s78
	s_add_i32 s20, s20, 1
	s_cmp_ge_i32 s8, s36
	s_cbranch_scc1 .Ltab8_wait
	s_and_b32 s15, s8, 0xff
	s_lshr_b32 s16, s8, 8
	s_movk_i32 s17, 0xe0
	s_cmp_eq_u32 s90, 3
	s_cselect_b32 s17, 0x100, s17
	s_mul_i32 s17, s16, s17
	s_add_i32 s17, s15, s17
	s_lshr_b32 s13, s17, 4
	s_and_b32 s14, s17, 15
	s_and_b64 vcc, exec, s[2:3]
	s_cbranch_vccz .Ltab8_r3
	s_min_i32 s15, s13, 64
	s_ashr_i32 s16, s15, 3
	s_ashr_i32 s17, s16, 31
	s_lshl_b32 s14, s14, 8
	s_ashr_i32 s15, s14, 31
	s_lshl_b64 s[16:17], s[16:17], 14
	s_add_u32 s16, s6, s16
	s_addc_u32 s17, s7, s17
	s_lshl_b64 s[14:15], s[14:15], 2
	s_add_u32 s14, s16, s14
	s_addc_u32 s15, s17, s15
	v_lshl_add_u64 v[2:3], v[192:193], 2, s[14:15]
	v_add_co_u32_e32 v2, vcc, 0x31cf000, v2
	s_nop 1
	v_addc_co_u32_e32 v3, vcc, 0, v3, vcc
	global_load_dword v64, v[2:3], off offset:3072
	s_branch .Ltab8_n3
.Ltab8_r3:
	v_lshl_add_u32 v2, s13, 8, v192
	v_ashrrev_i32_e32 v3, 31, v2
	v_lshlrev_b64 v[2:3], 6, v[2:3]
	v_lshl_add_u64 v[6:7], s[4:5], 0, v[2:3]
	global_load_dwordx4 v[64:67], v[6:7], off
	global_load_dwordx4 v[68:71], v[6:7], off offset:16
	global_load_dwordx4 v[72:75], v[6:7], off offset:32
	global_load_dwordx4 v[76:79], v[6:7], off offset:48
; __device__ __forceinline__ float rsq(float x) { return __builtin_amdgcn_rsqf(x); }
; template <class EpiT, class Sched>
; __device__ __forceinline__ void gemm_phase(LAS unsigned char* lds, const Gemm g, const Sched& S, const EpiT& E, int wv) {
;     ...
;     if constexpr (EpiT::TAB) {
;         Unit tu;
;         for (int i = 0; S.next(i, tu); ++i) {
;             if (tid < 256) { const f32x4* pp = (const f32x4*)(E.partr + (size_t)(tu.pm * BM + tid) * 16); const f32x4 p0 = pp[0], p1 = pp[1], p2 = pp[2], p3 = pp[3];
;                 const f32x4 ps = (p0 + p1) + (p2 + p3); tab[i * 512 + tid] = rsq(((ps[0] + ps[1]) + (ps[2] + ps[3])) * (1.f / DM) + EPS); }
;             else { const int mr = (tu.pm * BM < MX) ? ((tu.pm * BM) >> 11) : 8; tab[i * 512 + tid] = E.bias[(size_t)mr * E.bias_ld + tu.pn * BM + (tid - 256)]; }
;         }
.Ltab8_n3:
	s_add_u32 s8, s8, s60
	s_addc_u32 s9, s9, s78
	s_add_i32 s20, s20, 1
	s_cmp_ge_i32 s8, s36
	s_cbranch_scc1 .Ltab8_wait
	s_and_b32 s15, s8, 0xff
	s_lshr_b32 s16, s8, 8
	s_movk_i32 s17, 0xe0
	s_cmp_eq_u32 s90, 3
	s_cselect_b32 s17, 0x100, s17
	s_mul_i32 s17, s16, s17
	s_add_i32 s17, s15, s17
	s_lshr_b32 s13, s17, 4
	s_and_b32 s14, s17, 15
	s_and_b64 vcc, exec, s[2:3]
	s_cbranch_vccz .Ltab8_r4
	s_min_i32 s15, s13, 64
	s_ashr_i32 s16, s15, 3
	s_ashr_i32 s17, s16, 31
	s_lshl_b32 s14, s14, 8
	s_ashr_i32 s15, s14, 31
	s_lshl_b64 s[16:17], s[16:17], 14
	s_add_u32 s16, s6, s16
	s_addc_u32 s17, s7, s17
	s_lshl_b64 s[14:15], s[14:15], 2
	s_add_u32 s14, s16, s14
	s_addc_u32 s15, s17, s15
	v_lshl_add_u64 v[2:3], v[192:193], 2, s[14:15]
	v_add_co_u32_e32 v2, vcc, 0x31cf000, v2
	s_nop 1
	v_addc_co_u32_e32 v3, vcc, 0, v3, vcc
	global_load_dword v80, v[2:3], off offset:3072
	s_branch .Ltab8_n4
.Ltab8_r4:
	v_lshl_add_u32 v2, s13, 8, v192
	v_ashrrev_i32_e32 v3, 31, v2
	v_lshlrev_b64 v[2:3], 6, v[2:3]
	v_lshl_add_u64 v[6:7], s[4:5], 0, v[2:3]
	global_load_dwordx4 v[80:83], v[6:7], off
	global_load_dwordx4 v[84:87], v[6:7], off offset:16
	global_load_dwordx4 v[88:91], v[6:7], off offset:32
	global_load_dwordx4 v[92:95], v[6:7], off offset:48
.Ltab8_n4:
	s_add_u32 s8, s8, s60
	s_addc_u32 s9, s9, s78
	s_add_i32 s20, s20, 1
.Ltab8_wait:
	s_waitcnt vmcnt(0)
	s_cmp_le_u32 s20, 0
	s_cbranch_scc1 .Ltab8_done
	s_and_b64 vcc, exec, s[2:3]
	s_cbranch_vccnz .Ltab8_w0
	v_pk_add_f32 v[18:19], v[18:19], v[22:23]
	v_pk_add_f32 v[16:17], v[16:17], v[20:21]
	v_pk_add_f32 v[6:7], v[26:27], v[30:31]
	v_pk_add_f32 v[10:11], v[24:25], v[28:29]
	v_pk_add_f32 v[18:19], v[18:19], v[6:7]
	v_pk_add_f32 v[16:17], v[16:17], v[10:11]
	s_nop 0
	v_pk_mov_b32 v[6:7], v[16:17], v[18:19] op_sel:[1,0]
	v_mov_b32_e32 v17, v19
	v_pk_add_f32 v[16:17], v[6:7], v[16:17]
	s_nop 0
	v_add_f32_e32 v1, v16, v17
	v_fmamk_f32 v1, v1, 0x3a800000, v225
	v_rsq_f32_e32 v16, v1
.Ltab8_w0:
	ds_write_b32 v0, v16
	v_add_u32_e32 v0, 0x800, v0
	s_cmp_le_u32 s20, 1
	s_cbranch_scc1 .Ltab8_done
	s_and_b64 vcc, exec, s[2:3]
	s_cbranch_vccnz .Ltab8_w1
	v_pk_add_f32 v[34:35], v[34:35], v[38:39]
	v_pk_add_f32 v[32:33], v[32:33], v[36:37]
	v_pk_add_f32 v[6:7], v[42:43], v[46:47]
	v_pk_add_f32 v[10:11], v[40:41], v[44:45]
	v_pk_add_f32 v[34:35], v[34:35], v[6:7]
	v_pk_add_f32 v[32:33], v[32:33], v[10:11]
	s_nop 0
	v_pk_mov_b32 v[6:7], v[32:33], v[34:35] op_sel:[1,0]
	v_mov_b32_e32 v33, v35
	v_pk_add_f32 v[32:33], v[6:7], v[32:33]
	s_nop 0
	v_add_f32_e32 v1, v32, v33
	v_fmamk_f32 v1, v1, 0x3a800000, v225
	v_rsq_f32_e32 v32, v1
.Ltab8_w1:
	ds_write_b32 v0, v32
	v_add_u32_e32 v0, 0x800, v0
	s_cmp_le_u32 s20, 2
	s_cbranch_scc1 .Ltab8_done
	s_and_b64 vcc, exec, s[2:3]
	s_cbranch_vccnz .Ltab8_w2
	v_pk_add_f32 v[50:51], v[50:51], v[54:55]
	v_pk_add_f32 v[48:49], v[48:49], v[52:53]
	v_pk_add_f32 v[6:7], v[58:59], v[62:63]
	v_pk_add_f32 v[10:11], v[56:57], v[60:61]
	v_pk_add_f32 v[50:51], v[50:51], v[6:7]
	v_pk_add_f32 v[48:49], v[48:49], v[10:11]
	s_nop 0
	v_pk_mov_b32 v[6:7], v[48:49], v[50:51] op_sel:[1,0]
	v_mov_b32_e32 v49, v51
	v_pk_add_f32 v[48:49], v[6:7], v[48:49]
	s_nop 0
	v_add_f32_e32 v1, v48, v49
	v_fmamk_f32 v1, v1, 0x3a800000, v225
	v_rsq_f32_e32 v48, v1
.Ltab8_w2:
	ds_write_b32 v0, v48
	v_add_u32_e32 v0, 0x800, v0
	s_cmp_le_u32 s20, 3
	s_cbranch_scc1 .Ltab8_done
	s_and_b64 vcc, exec, s[2:3]
	s_cbranch_vccnz .Ltab8_w3
	v_pk_add_f32 v[66:67], v[66:67], v[70:71]
	v_pk_add_f32 v[64:65], v[64:65], v[68:69]
	v_pk_add_f32 v[6:7], v[74:75], v[78:79]
	v_pk_add_f32 v[10:11], v[72:73], v[76:77]
	v_pk_add_f32 v[66:67], v[66:67], v[6:7]
	v_pk_add_f32 v[64:65], v[64:65], v[10:11]
	s_nop 0
	v_pk_mov_b32 v[6:7], v[64:65], v[66:67] op_sel:[1,0]
	v_mov_b32_e32 v65, v67
	v_pk_add_f32 v[64:65], v[6:7], v[64:65]
	s_nop 0
	v_add_f32_e32 v1, v64, v65
	v_fmamk_f32 v1, v1, 0x3a800000, v225
	v_rsq_f32_e32 v64, v1
.Ltab8_w3:
	ds_write_b32 v0, v64
	v_add_u32_e32 v0, 0x800, v0
	s_cmp_le_u32 s20, 4
	s_cbranch_scc1 .Ltab8_done
	s_and_b64 vcc, exec, s[2:3]
	s_cbranch_vccnz .Ltab8_w4
	v_pk_add_f32 v[82:83], v[82:83], v[86:87]
	v_pk_add_f32 v[80:81], v[80:81], v[84:85]
	v_pk_add_f32 v[6:7], v[90:91], v[94:95]
	v_pk_add_f32 v[10:11], v[88:89], v[92:93]
	v_pk_add_f32 v[82:83], v[82:83], v[6:7]
	v_pk_add_f32 v[80:81], v[80:81], v[10:11]
	s_nop 0
	v_pk_mov_b32 v[6:7], v[80:81], v[82:83] op_sel:[1,0]
	v_mov_b32_e32 v81, v83
	v_pk_add_f32 v[80:81], v[6:7], v[80:81]
	s_nop 0
	v_add_f32_e32 v1, v80, v81
	v_fmamk_f32 v1, v1, 0x3a800000, v225
	v_rsq_f32_e32 v80, v1
.Ltab8_w4:
	ds_write_b32 v0, v80
	v_add_u32_e32 v0, 0x800, v0
;     __device__ bool next(int i, Unit& u) const {
;     ...
;         int wgid = (int)L; { const int q = nwg / NXCD, r = nwg % NXCD, xcd = wgid % NXCD, off = wgid / NXCD; wgid = (xcd < r ? xcd * (q + 1) : r * (q + 1) + (xcd - r) * q) + off; }
;         const int nig = WGM * nN, gid = wgid / nig, fm = gid * WGM, gsz = (nM - fm) < WGM ? (nM - fm) : WGM;
;         u.pm = fm + ((wgid % nig) % gsz); u.pn = (wgid % nig) / gsz; return true;
; template <class EpiT, class Sched>
; __device__ __forceinline__ void gemm_phase(LAS unsigned char* lds, const Gemm g, const Sched& S, const EpiT& E, int wv) {
;     ...
;     for (int i = 0; i < 2; ++i) { int R, C; stage_rc(tid * 16 + i * 8192, R, C); const int Rb = EpiT::PERM ? ((R & ~31) + perm32(R & 31)) : R;
;         voffA[i] = (unsigned)(R * g.lda + C) * 2u; voffB[i] = (unsigned)(Rb * g.ldb + C) * 2u; }
;     const size_t kstep = (size_t)(BK * 2);
;     const size_t hstepA = (size_t)HALF * g.lda * 2, hstepB = (size_t)HALF * g.ldb * 2;
;     const size_t tstepA = 2 * hstepA, tstepB = 2 * hstepB;
;     const unsigned ldsw = (unsigned)wid * 1024u;
;     const int foff = lds_byte(fr, fq * 8);
;     const int aoff = wr * 8192 + foff, boff = wc * 4096 + foff;
;     ...
;     Unit cur, nxt; int ui = 0;
;     if (!S.next(0, cur)) return;
;     if constexpr (EpiT::TAB) {
;         Unit tu;
;         for (int i = 0; S.next(i, tu); ++i) {
;             if (tid < 256) { const f32x4* pp = (const f32x4*)(E.partr + (size_t)(tu.pm * BM + tid) * 16); const f32x4 p0 = pp[0], p1 = pp[1], p2 = pp[2], p3 = pp[3];
;                 const f32x4 ps = (p0 + p1) + (p2 + p3); tab[i * 512 + tid] = rsq(((ps[0] + ps[1]) + (ps[2] + ps[3])) * (1.f / DM) + EPS); }
;             else { const int mr = (tu.pm * BM < MX) ? ((tu.pm * BM) >> 11) : 8; tab[i * 512 + tid] = E.bias[(size_t)mr * E.bias_ld + tu.pn * BM + (tid - 256)]; }
;         }
;         __syncthreads();
;     }
;     f32x4 acc[2][2][4][2];
; #pragma unroll
;     for (int a = 0; a < 2; ++a)
; #pragma unroll
;         for (int b = 0; b < 2; ++b)
; #pragma unroll
;             for (int m = 0; m < 4; ++m)
; #pragma unroll
;                 for (int n = 0; n < 2; ++n) acc[a][b][m][n] = (f32x4){0.f, 0.f, 0.f, 0.f};
;     bf16x8 At[4][2], B0[2][2], B1[2][2];
;     const char* cA = (const char*)g.A + (size_t)cur.pm * tstepA + (size_t)(cur.pn >> g.zshift) * g.zA; const char* cB = (const char*)g.Bt + (size_t)cur.pn * tstepB;
.Ltab8_done:
.LBB0_1263:
	s_ashr_i32 s2, s0, 31
	s_lshr_b32 s2, s2, 29
	s_add_i32 s2, s0, s2
	s_ashr_i32 s3, s2, 3
	s_and_b32 s2, s2, -8
	s_sub_i32 s2, s0, s2
	s_cmp_lt_i32 s2, 0
	s_cselect_b32 s4, s44, s43
	s_mul_i32 s2, s2, s4
	s_add_i32 s2, s2, s3
	s_ashr_i32 s3, s2, 31
	s_lshr_b32 s3, s3, 25
	s_add_i32 s3, s2, s3
	s_ashr_i32 s4, s3, 7
	s_lshl_b32 s4, s4, 3
	s_sub_i32 s5, s42, s4
	s_min_i32 s5, s5, 8
	s_abs_i32 s8, s5
	v_cvt_f32_u32_e32 v0, s8
	s_sub_i32 s10, 0, s8
	v_ashrrev_i32_e32 v1, 31, v192
	s_and_b32 s3, s3, 0xffffff80
	v_rcp_iflag_f32_e32 v0, v0
	v_lshrrev_b32_e32 v1, 26, v1
	s_sub_i32 s2, s2, s3
	v_add_u32_e32 v1, v192, v1
	v_mul_f32_e32 v0, 0x4f7ffffe, v0
	v_cvt_u32_f32_e32 v0, v0
	s_abs_i32 s3, s2
	v_ashrrev_i32_e32 v9, 6, v1
	v_bfe_i32 v1, v192, 27, 1
	v_readfirstlane_b32 s11, v0
	s_mul_i32 s10, s10, s11
	s_mul_hi_u32 s10, s11, s10
	s_add_i32 s11, s11, s10
	s_mul_hi_u32 s10, s3, s11
	v_lshlrev_b32_e32 v0, 4, v192
	v_lshrrev_b32_e32 v1, 22, v1
	s_mul_i32 s11, s10, s8
	v_add_u32_e32 v1, v0, v1
	s_xor_b32 s9, s2, s5
	s_sub_i32 s3, s3, s11
	v_and_b32_e32 v1, 0xfffffc00, v1
	s_ashr_i32 s9, s9, 31
	s_add_i32 s13, s10, 1
	s_sub_i32 s11, s3, s8
	v_sub_u32_e32 v1, v0, v1
	s_cmp_ge_u32 s3, s8
	v_lshrrev_b32_e32 v2, 4, v1
	s_cselect_b32 s10, s13, s10
	v_bitop3_b32 v1, v2, v1, 32 bitop3:0x6c
	s_cselect_b32 s3, s11, s3
	s_add_i32 s11, s10, 1
	v_ashrrev_i32_e32 v3, 31, v1
	s_cmp_ge_u32 s3, s8
	v_lshrrev_b32_e32 v3, 26, v3
	s_cselect_b32 s3, s11, s10
	v_add_u32_e32 v3, v1, v3
	s_xor_b32 s3, s3, s9
	v_lshlrev_b32_e32 v2, 3, v9
	v_ashrrev_i32_e32 v10, 6, v3
	v_and_b32_e32 v3, 0xc0, v3
	s_sub_i32 s18, s3, s9
	v_and_b32_e32 v2, -16, v2
	v_sub_u32_e32 v1, v1, v3
	s_mul_i32 s3, s18, s5
	v_add_u32_e32 v2, v10, v2
	v_ashrrev_i16_sdwa v1, v224, sext(v1) dst_sel:DWORD dst_unused:UNUSED_PAD src0_sel:DWORD src1_sel:BYTE_0
	s_sub_i32 s2, s2, s3
	v_lshlrev_b32_e32 v4, 5, v9
	v_bfe_i32 v11, v1, 0, 16
	v_lshlrev_b32_e32 v1, 1, v2
	v_lshrrev_b32_e32 v3, 2, v2
	v_and_b32_e32 v5, 3, v10
	s_mov_b32 s3, 0x1fffe0
	v_and_b32_e32 v4, 32, v4
	v_and_b32_e32 v1, 24, v1
	v_and_b32_e32 v3, 4, v3
	v_and_or_b32 v5, v2, s3, v5
	v_or3_b32 v1, v5, v3, v1
	v_add_lshl_u32 v3, v4, v11, 1
	v_add_u32_e32 v0, 0x2000, v0
	v_lshl_add_u32 v192, v1, 11, v3
	v_ashrrev_i32_e32 v1, 31, v0
	v_lshrrev_b32_e32 v1, 22, v1
	v_add_u32_e32 v1, v0, v1
	v_ashrrev_i32_e32 v12, 10, v1
	v_mul_i32_i24_e32 v1, 0x400, v12
	v_sub_u32_e32 v0, v0, v1
	v_lshrrev_b32_e32 v1, 4, v0
	v_bitop3_b32 v0, v1, v0, 32 bitop3:0x6c
	s_add_i32 s20, s4, s2
	s_lshr_b32 s20, s79, 4
	s_and_b32 s18, s79, 15
	v_lshl_add_u32 v136, v2, 11, v3
	v_ashrrev_i32_e32 v2, 31, v0
	s_add_u32 s28, s6, 0x3c00000
	v_lshrrev_b32_e32 v2, 26, v2
	s_addc_u32 s29, s7, 0
	v_lshlrev_b32_e32 v1, 3, v12
	v_add_u32_e32 v2, v0, v2
	s_add_u32 s30, s6, 0x1f00000
	v_and_b32_e32 v1, -16, v1
	v_ashrrev_i32_e32 v13, 6, v2
	s_addc_u32 s31, s7, 0
	s_ashr_i32 s2, s12, 6
	v_add_u32_e32 v1, v13, v1
	v_and_b32_e32 v2, 0xc0, v2
	v_and_b32_e32 v4, 3, v13
	s_ashr_i32 s21, s20, 31
	s_ashr_i32 s19, s18, 31
	v_sub_u32_e32 v0, v0, v2
	v_and_or_b32 v4, v1, s3, v4
	s_ashr_i32 s3, s12, 8
	s_lshl_b32 s33, s2, 10
	s_lshl_b64 s[4:5], s[20:21], 19
	s_lshl_b64 s[8:9], s[18:19], 19
	v_ashrrev_i16_sdwa v0, v224, sext(v0) dst_sel:DWORD dst_unused:UNUSED_PAD src0_sel:DWORD src1_sel:BYTE_0
	s_add_u32 s24, s30, s8
	v_lshlrev_b32_e32 v3, 5, v12
	v_bfe_i32 v14, v0, 0, 16
	v_lshlrev_b32_e32 v0, 1, v1
	v_lshrrev_b32_e32 v2, 2, v1
	s_addc_u32 s25, s31, s9
	s_add_i32 s19, s33, 0
	v_and_b32_e32 v3, 32, v3
	v_and_b32_e32 v0, 24, v0
	v_and_b32_e32 v2, 4, v2
	s_add_i32 m0, s19, 0x10000
	v_or3_b32 v0, v4, v2, v0
	v_add_lshl_u32 v2, v3, v14, 1
	s_waitcnt lgkmcnt(0)
	s_barrier
	global_load_lds_dwordx4 v192, s[24:25]
	s_add_i32 m0, s19, 0x12000
	v_lshl_add_u32 v140, v0, 11, v2
	s_add_u32 s8, s24, 0x40000
	global_load_lds_dwordx4 v140, s[24:25]
	s_addc_u32 s9, s25, 0
	s_add_i32 m0, s19, 0x14000
	v_lshl_add_u32 v138, v1, 11, v2
	global_load_lds_dwordx4 v192, s[8:9]
	s_add_i32 m0, s19, 0x16000
	s_add_u32 s22, s28, s4
	s_addc_u32 s23, s29, s5
	s_add_i32 s21, s19, 0x2000
	global_load_lds_dwordx4 v140, s[8:9]
	s_mov_b32 m0, s19
	s_add_u32 s4, s22, 0x40000
	global_load_lds_dwordx4 v136, s[22:23]
	s_mov_b32 m0, s21
	s_addc_u32 s5, s23, 0
	s_add_i32 s38, s19, 0x4000
	global_load_lds_dwordx4 v138, s[22:23]
	s_mov_b32 m0, s38
	s_add_i32 s39, s19, 0x6000
	global_load_lds_dwordx4 v136, s[4:5]
	s_mov_b32 m0, s39
	s_cmp_eq_u32 s3, 1
	global_load_lds_dwordx4 v138, s[4:5]
	v_mov_b32_e32 v141, v193
	v_mov_b32_e32 v137, v193
	v_mov_b32_e32 v139, v193
	s_cselect_b64 s[4:5], -1, 0
	v_lshl_add_u64 v[6:7], s[24:25], 0, v[192:193]
	v_lshl_add_u64 v[4:5], s[24:25], 0, v[140:141]
	v_lshl_add_u64 v[2:3], s[22:23], 0, v[136:137]
	v_lshl_add_u64 v[0:1], s[22:23], 0, v[138:139]
	s_and_b64 vcc, exec, s[4:5]
	s_cbranch_vccz .LBB0_1265
	s_barrier
